# GEMM rope epilogue: cos/sin tables staged once per phase into free LDS (0x20000..0x23000) and read with ds_read_b128; the 48 s_waitcnt vmcnt(0) that also drained epilogue stores become lgkmcnt(0); on
# speedup vs baseline: 1.0215x; 1.0079x over previous
.LBB0_259:
	s_mov_b32 s98, 0x20000
	s_mov_b32 s99, 0x22000
	s_cmp_eq_u32 s56, 0
	s_cbranch_scc1 .Lrope_fill
	s_cmp_eq_u32 s56, 22
	s_cbranch_scc1 .Lrope_fill
	s_cmp_eq_u32 s56, 30
	s_cbranch_scc0 .Lrope_nofill
.Lrope_fill:
	v_readlane_b32 s100, v244, 4
	v_readlane_b32 s101, v244, 5
	s_add_u32 s100, s100, 0x100000
	s_addc_u32 s101, s101, 0
	v_lshlrev_b32_e32 v236, 4, v147
	s_nop 3
	global_load_dwordx4 v[224:227], v236, s[100:101]
	v_add_u32_e32 v237, s98, v236
	s_add_u32 s100, s100, 0x2000
	s_addc_u32 s101, s101, 0
	v_and_b32_e32 v238, 0xfff, v236
	s_nop 3
	global_load_dwordx4 v[228:231], v238, s[100:101]
	v_add_u32_e32 v238, s99, v238
	s_waitcnt vmcnt(1)
	ds_write_b128 v237, v[224:227]
	s_waitcnt vmcnt(0)
	ds_write_b128 v238, v[228:231]
	s_waitcnt lgkmcnt(0)
	s_barrier

.LBB0_750:
	v_mov_b64_e32 v[128:129], v[120:121]
	s_andn2_b64 vcc, exec, s[40:41]
	v_mov_b64_e32 v[126:127], v[118:119]
	v_mov_b64_e32 v[124:125], v[116:117]
	v_mov_b64_e32 v[122:123], v[114:115]
	s_cbranch_vccnz .LBB0_752
	v_and_b32_e32 v122, 32, v167
	v_cmp_eq_u32_e32 vcc, 0, v122
	v_lshlrev_b32_e32 v123, 2, v0
	s_nop 0
	v_cndmask_b32_e32 v122, v169, v170, vcc
	v_cmp_lt_i32_e32 vcc, v198, v200
	v_lshl_or_b32 v122, v122, 7, v123
	s_nop 0
	v_cndmask_b32_e32 v123, v197, v198, vcc
	v_lshlrev_b32_e32 v161, 2, v123
	v_add_u32_e32 v122, s98, v122
	ds_read_b128 v[174:177], v122 offset:48
	ds_read_b128 v[126:129], v122 offset:32
	ds_read_b128 v[178:181], v122 offset:16
	s_nop 0
	ds_read_b128 v[122:125], v122
	ds_bpermute_b32 v162, v161, v114
	ds_bpermute_b32 v163, v161, v115
	s_waitcnt lgkmcnt(0)
	v_mov_b32_e32 v183, v124
	v_mov_b32_e32 v124, v123
	v_mov_b32_e32 v182, v122
	s_waitcnt lgkmcnt(0)
	v_pk_mul_f32 v[122:123], v[124:125], v[162:163]
	ds_bpermute_b32 v124, v161, v116
	ds_bpermute_b32 v125, v161, v117
	v_mov_b32_e32 v163, v180
	v_mov_b32_e32 v180, v179
	v_mov_b32_e32 v162, v178
	v_mov_b32_e32 v179, v128
	s_waitcnt lgkmcnt(0)
	v_pk_mul_f32 v[124:125], v[180:181], v[124:125]
	v_mov_b32_e32 v128, v127
	v_cndmask_b32_e64 v125, v125, -v125, s[38:39]
	v_cndmask_b32_e64 v124, v124, -v124, s[38:39]
	v_pk_fma_f32 v[124:125], v[116:117], v[162:163], v[124:125]
	ds_bpermute_b32 v162, v161, v118
	ds_bpermute_b32 v163, v161, v119
	v_mov_b32_e32 v178, v126
	v_cndmask_b32_e64 v123, v123, -v123, s[38:39]
	v_cndmask_b32_e64 v122, v122, -v122, s[38:39]
	v_pk_fma_f32 v[122:123], v[114:115], v[182:183], v[122:123]
	s_waitcnt lgkmcnt(0)
	v_pk_mul_f32 v[126:127], v[128:129], v[162:163]
	ds_bpermute_b32 v128, v161, v120
	ds_bpermute_b32 v129, v161, v121
	v_mov_b32_e32 v163, v176
	v_mov_b32_e32 v176, v175
	v_cndmask_b32_e64 v127, v127, -v127, s[38:39]
	v_cndmask_b32_e64 v126, v126, -v126, s[38:39]
	s_waitcnt lgkmcnt(0)
	v_pk_mul_f32 v[128:129], v[176:177], v[128:129]
	v_mov_b32_e32 v162, v174
	v_cndmask_b32_e64 v129, v129, -v129, s[38:39]
	v_cndmask_b32_e64 v128, v128, -v128, s[38:39]
	v_pk_fma_f32 v[126:127], v[118:119], v[178:179], v[126:127]
	v_pk_fma_f32 v[128:129], v[120:121], v[162:163], v[128:129]

.LBB0_754:
	v_readlane_b32 s6, v241, 47
	v_cndmask_b32_e64 v161, v169, v170, s[38:39]
	v_readlane_b32 s7, v241, 48
	v_lshlrev_b32_e32 v173, 4, v161
	v_cndmask_b32_e64 v161, 0, 1, s[40:41]
	s_and_b64 s[0:1], s[6:7], s[0:1]
	s_and_b64 vcc, exec, vcc
	v_cmp_ne_u32_e64 s[40:41], 1, v161
	s_cbranch_vccz .LBB0_763
	s_and_b64 vcc, exec, s[40:41]
	s_cbranch_vccnz .LBB0_757
	v_and_b32_e32 v122, 32, v167
	v_cmp_eq_u32_e32 vcc, 0, v122
	v_lshlrev_b32_e32 v123, 2, v0
	s_nop 0
	v_cndmask_b32_e32 v122, v169, v170, vcc
	v_cmp_lt_i32_e32 vcc, v198, v200
	v_lshl_or_b32 v174, v122, 7, v123
	s_nop 0
	v_cndmask_b32_e32 v122, v197, v198, vcc
	v_lshlrev_b32_e32 v182, 2, v122
	v_add_u32_e32 v174, s98, v174
	ds_read_b128 v[122:125], v174 offset:48
	ds_read_b128 v[126:129], v174 offset:32
	ds_read_b128 v[160:163], v174 offset:16
	s_nop 0
	ds_read_b128 v[174:177], v174
	ds_bpermute_b32 v178, v182, v114
	ds_bpermute_b32 v179, v182, v115
	s_waitcnt lgkmcnt(0)
	v_mov_b32_e32 v181, v176
	v_mov_b32_e32 v176, v175
	v_mov_b32_e32 v180, v174
	s_waitcnt lgkmcnt(0)
	v_pk_mul_f32 v[174:175], v[176:177], v[178:179]
	v_mov_b32_e32 v177, v162
	v_cndmask_b32_e64 v175, v175, -v175, s[38:39]
	v_cndmask_b32_e64 v174, v174, -v174, s[38:39]
	v_pk_fma_f32 v[114:115], v[114:115], v[180:181], v[174:175]
	ds_bpermute_b32 v174, v182, v116
	ds_bpermute_b32 v175, v182, v117
	v_mov_b32_e32 v162, v161
	v_mov_b32_e32 v176, v160
	s_waitcnt lgkmcnt(0)
	v_pk_mul_f32 v[160:161], v[162:163], v[174:175]
	s_nop 0
	v_cndmask_b32_e64 v161, v161, -v161, s[38:39]
	v_cndmask_b32_e64 v160, v160, -v160, s[38:39]
	v_pk_fma_f32 v[116:117], v[116:117], v[176:177], v[160:161]
	ds_bpermute_b32 v160, v182, v118
	ds_bpermute_b32 v161, v182, v119
	v_mov_b32_e32 v163, v128
	v_mov_b32_e32 v128, v127
	v_mov_b32_e32 v162, v126
	s_waitcnt lgkmcnt(0)
	v_pk_mul_f32 v[126:127], v[128:129], v[160:161]
	s_nop 0
	v_cndmask_b32_e64 v127, v127, -v127, s[38:39]
	v_cndmask_b32_e64 v126, v126, -v126, s[38:39]
	v_pk_fma_f32 v[118:119], v[118:119], v[162:163], v[126:127]
	ds_bpermute_b32 v126, v182, v120
	ds_bpermute_b32 v127, v182, v121
	v_mov_b32_e32 v129, v124
	v_mov_b32_e32 v124, v123
	v_mov_b32_e32 v128, v122
	s_waitcnt lgkmcnt(0)
	v_pk_mul_f32 v[122:123], v[124:125], v[126:127]
	s_nop 0
	v_cndmask_b32_e64 v123, v123, -v123, s[38:39]
	v_cndmask_b32_e64 v122, v122, -v122, s[38:39]
	v_pk_fma_f32 v[120:121], v[120:121], v[128:129], v[122:123]
.LBB0_757:
	s_andn2_b64 vcc, exec, s[0:1]
	s_cbranch_vccnz .LBB0_760
	s_lshl_b32 s6, s91, 3
	v_readlane_b32 s7, v241, 60
	s_or_b32 s6, s6, s7
	s_mul_hi_i32 s7, s6, 0x55555556
	s_lshr_b32 vcc_lo, s7, 31
	s_add_i32 s7, s7, vcc_lo
	s_mul_i32 s7, s7, 3
	s_sub_i32 s6, s6, s7
	s_cmp_lg_u32 s6, 2
	s_cbranch_scc1 .LBB0_760
	v_xor_b32_e32 v122, 16, v197
	v_cmp_lt_i32_e32 vcc, v122, v200
	v_lshlrev_b32_e32 v174, 2, v173
	s_nop 0
	v_cndmask_b32_e32 v122, v197, v122, vcc
	v_lshlrev_b32_e32 v182, 2, v122
	v_add_u32_e32 v174, s99, v174
	ds_read_b128 v[122:125], v174 offset:48
	ds_read_b128 v[126:129], v174 offset:32
	ds_read_b128 v[160:163], v174 offset:16
	s_nop 0
	ds_read_b128 v[174:177], v174
	ds_bpermute_b32 v178, v182, v114
	ds_bpermute_b32 v179, v182, v115
	s_waitcnt lgkmcnt(0)
	v_mov_b32_e32 v181, v176
	v_mov_b32_e32 v176, v175
	v_mov_b32_e32 v180, v174
	s_waitcnt lgkmcnt(0)
	v_pk_mul_f32 v[174:175], v[176:177], v[178:179]
	v_mov_b32_e32 v177, v162
	v_cndmask_b32_e64 v175, v175, -v175, s[36:37]
	v_cndmask_b32_e64 v174, v174, -v174, s[36:37]
	v_pk_fma_f32 v[114:115], v[114:115], v[180:181], v[174:175]
	ds_bpermute_b32 v174, v182, v116
	ds_bpermute_b32 v175, v182, v117
	v_mov_b32_e32 v162, v161
	v_mov_b32_e32 v176, v160
	s_waitcnt lgkmcnt(0)
	v_pk_mul_f32 v[160:161], v[162:163], v[174:175]
	s_nop 0
	v_cndmask_b32_e64 v161, v161, -v161, s[36:37]
	v_cndmask_b32_e64 v160, v160, -v160, s[36:37]
	v_pk_fma_f32 v[116:117], v[116:117], v[176:177], v[160:161]
	ds_bpermute_b32 v160, v182, v118
	ds_bpermute_b32 v161, v182, v119
	v_mov_b32_e32 v163, v128
	v_mov_b32_e32 v128, v127
	v_mov_b32_e32 v162, v126
	s_waitcnt lgkmcnt(0)
	v_pk_mul_f32 v[126:127], v[128:129], v[160:161]
	s_nop 0
	v_cndmask_b32_e64 v127, v127, -v127, s[36:37]
	v_cndmask_b32_e64 v126, v126, -v126, s[36:37]
	v_pk_fma_f32 v[118:119], v[118:119], v[162:163], v[126:127]
	ds_bpermute_b32 v126, v182, v120
	ds_bpermute_b32 v127, v182, v121
	v_mov_b32_e32 v129, v124
	v_mov_b32_e32 v124, v123
	v_mov_b32_e32 v128, v122
	s_waitcnt lgkmcnt(0)
	v_pk_mul_f32 v[122:123], v[124:125], v[126:127]
	s_nop 0
	v_cndmask_b32_e64 v123, v123, -v123, s[36:37]
	v_cndmask_b32_e64 v122, v122, -v122, s[36:37]
	v_pk_fma_f32 v[120:121], v[120:121], v[128:129], v[122:123]

.LBB0_768:
	v_mov_b64_e32 v[120:121], v[112:113]
	s_and_b64 vcc, exec, s[40:41]
	v_mov_b64_e32 v[118:119], v[110:111]
	v_mov_b64_e32 v[116:117], v[108:109]
	v_mov_b64_e32 v[114:115], v[106:107]
	s_cbranch_vccnz .LBB0_770
	v_and_b32_e32 v114, 32, v167
	v_cmp_eq_u32_e32 vcc, 0, v114
	v_lshlrev_b32_e32 v115, 2, v0
	s_nop 0
	v_cndmask_b32_e32 v114, v169, v170, vcc
	v_cmp_lt_i32_e32 vcc, v198, v200
	v_lshl_or_b32 v114, v114, 7, v115
	s_nop 0
	v_cndmask_b32_e32 v115, v197, v198, vcc
	v_lshlrev_b32_e32 v123, 2, v115
	v_add_u32_e32 v114, s98, v114
	ds_read_b128 v[160:163], v114 offset:48
	ds_read_b128 v[118:121], v114 offset:32
	ds_read_b128 v[174:177], v114 offset:16
	s_nop 0
	ds_read_b128 v[114:117], v114
	ds_bpermute_b32 v128, v123, v106
	ds_bpermute_b32 v129, v123, v107
	s_waitcnt lgkmcnt(0)
	v_mov_b32_e32 v179, v116
	v_mov_b32_e32 v116, v115
	v_mov_b32_e32 v178, v114
	s_waitcnt lgkmcnt(0)
	v_pk_mul_f32 v[114:115], v[116:117], v[128:129]
	ds_bpermute_b32 v116, v123, v108
	ds_bpermute_b32 v117, v123, v109
	v_mov_b32_e32 v129, v176
	v_mov_b32_e32 v176, v175
	v_mov_b32_e32 v128, v174
	v_mov_b32_e32 v175, v120
	s_waitcnt lgkmcnt(0)
	v_pk_mul_f32 v[116:117], v[176:177], v[116:117]
	v_mov_b32_e32 v120, v119
	v_cndmask_b32_e64 v117, v117, -v117, s[38:39]
	v_cndmask_b32_e64 v116, v116, -v116, s[38:39]
	v_pk_fma_f32 v[116:117], v[108:109], v[128:129], v[116:117]
	ds_bpermute_b32 v128, v123, v110
	ds_bpermute_b32 v129, v123, v111
	v_mov_b32_e32 v174, v118
	v_cndmask_b32_e64 v115, v115, -v115, s[38:39]
	v_cndmask_b32_e64 v114, v114, -v114, s[38:39]
	v_pk_fma_f32 v[114:115], v[106:107], v[178:179], v[114:115]
	s_waitcnt lgkmcnt(0)
	v_pk_mul_f32 v[118:119], v[120:121], v[128:129]
	ds_bpermute_b32 v120, v123, v112
	ds_bpermute_b32 v121, v123, v113
	v_mov_b32_e32 v129, v162
	v_mov_b32_e32 v162, v161
	v_cndmask_b32_e64 v119, v119, -v119, s[38:39]
	v_cndmask_b32_e64 v118, v118, -v118, s[38:39]
	s_waitcnt lgkmcnt(0)
	v_pk_mul_f32 v[120:121], v[162:163], v[120:121]
	v_mov_b32_e32 v128, v160
	v_cndmask_b32_e64 v121, v121, -v121, s[38:39]
	v_cndmask_b32_e64 v120, v120, -v120, s[38:39]
	v_pk_fma_f32 v[118:119], v[110:111], v[174:175], v[118:119]
	v_pk_fma_f32 v[120:121], v[112:113], v[128:129], v[120:121]

.LBB0_771:
	s_mov_b64 s[10:11], 0
	s_cbranch_execz .LBB0_780
	s_and_b64 vcc, exec, s[40:41]
	s_cbranch_vccnz .LBB0_774
	v_and_b32_e32 v114, 32, v167
	v_cmp_eq_u32_e32 vcc, 0, v114
	v_lshlrev_b32_e32 v115, 2, v0
	s_nop 0
	v_cndmask_b32_e32 v114, v169, v170, vcc
	v_cmp_lt_i32_e32 vcc, v198, v200
	v_lshl_or_b32 v123, v114, 7, v115
	s_nop 0
	v_cndmask_b32_e32 v114, v197, v198, vcc
	v_lshlrev_b32_e32 v125, 2, v114
	v_add_u32_e32 v123, s98, v123
	ds_read_b128 v[114:117], v123 offset:48
	ds_read_b128 v[118:121], v123 offset:32
	ds_read_b128 v[126:129], v123 offset:16
	ds_read_b128 v[160:163], v123
	v_subrev_u32_e32 v123, s98, v123
	ds_bpermute_b32 v170, v125, v106
	ds_bpermute_b32 v171, v125, v107
	s_waitcnt lgkmcnt(0)
	v_mov_b32_e32 v175, v162
	v_mov_b32_e32 v162, v161
	v_mov_b32_e32 v174, v160
	s_waitcnt lgkmcnt(0)
	v_pk_mul_f32 v[160:161], v[162:163], v[170:171]
	v_mov_b32_e32 v163, v128
	v_cndmask_b32_e64 v161, v161, -v161, s[38:39]
	v_cndmask_b32_e64 v160, v160, -v160, s[38:39]
	v_pk_fma_f32 v[106:107], v[106:107], v[174:175], v[160:161]
	ds_bpermute_b32 v160, v125, v108
	ds_bpermute_b32 v161, v125, v109
	v_mov_b32_e32 v128, v127
	v_mov_b32_e32 v162, v126
	s_waitcnt lgkmcnt(0)
	v_pk_mul_f32 v[126:127], v[128:129], v[160:161]
	s_nop 0
	v_cndmask_b32_e64 v127, v127, -v127, s[38:39]
	v_cndmask_b32_e64 v126, v126, -v126, s[38:39]
	v_pk_fma_f32 v[108:109], v[108:109], v[162:163], v[126:127]
	ds_bpermute_b32 v126, v125, v110
	ds_bpermute_b32 v127, v125, v111
	v_mov_b32_e32 v129, v120
	v_mov_b32_e32 v120, v119
	v_mov_b32_e32 v128, v118
	s_waitcnt lgkmcnt(0)
	v_pk_mul_f32 v[118:119], v[120:121], v[126:127]
	s_nop 0
	v_cndmask_b32_e64 v119, v119, -v119, s[38:39]
	v_cndmask_b32_e64 v118, v118, -v118, s[38:39]
	v_pk_fma_f32 v[110:111], v[110:111], v[128:129], v[118:119]
	ds_bpermute_b32 v118, v125, v112
	ds_bpermute_b32 v119, v125, v113
	v_mov_b32_e32 v121, v116
	v_mov_b32_e32 v116, v115
	v_mov_b32_e32 v120, v114
	s_waitcnt lgkmcnt(0)
	v_pk_mul_f32 v[114:115], v[116:117], v[118:119]
	s_nop 0
	v_cndmask_b32_e64 v115, v115, -v115, s[38:39]
	v_cndmask_b32_e64 v114, v114, -v114, s[38:39]
	v_pk_fma_f32 v[112:113], v[112:113], v[120:121], v[114:115]
.LBB0_774:
	s_andn2_b64 vcc, exec, s[0:1]
	s_cbranch_vccnz .LBB0_777
	s_lshl_b32 s6, s91, 3
	v_readlane_b32 s7, v241, 61
	s_or_b32 s6, s6, s7
	s_mul_hi_i32 s7, s6, 0x55555556
	s_lshr_b32 vcc_lo, s7, 31
	s_add_i32 s7, s7, vcc_lo
	s_mul_i32 s7, s7, 3
	s_sub_i32 s6, s6, s7
	s_cmp_lg_u32 s6, 2
	s_cbranch_scc1 .LBB0_777
	v_xor_b32_e32 v114, 16, v197
	v_cmp_lt_i32_e32 vcc, v114, v200
	v_lshlrev_b32_e32 v123, 2, v173
	s_nop 0
	v_cndmask_b32_e32 v114, v197, v114, vcc
	v_lshlrev_b32_e32 v125, 2, v114
	v_add_u32_e32 v123, s99, v123
	ds_read_b128 v[114:117], v123 offset:48
	ds_read_b128 v[118:121], v123 offset:32
	ds_read_b128 v[126:129], v123 offset:16
	ds_read_b128 v[160:163], v123
	v_subrev_u32_e32 v123, s99, v123
	ds_bpermute_b32 v170, v125, v106
	ds_bpermute_b32 v171, v125, v107
	s_waitcnt lgkmcnt(0)
	v_mov_b32_e32 v173, v162
	v_mov_b32_e32 v162, v161
	v_mov_b32_e32 v172, v160
	s_waitcnt lgkmcnt(0)
	v_pk_mul_f32 v[160:161], v[162:163], v[170:171]
	v_mov_b32_e32 v163, v128
	v_cndmask_b32_e64 v161, v161, -v161, s[36:37]
	v_cndmask_b32_e64 v160, v160, -v160, s[36:37]
	v_pk_fma_f32 v[106:107], v[106:107], v[172:173], v[160:161]
	ds_bpermute_b32 v160, v125, v108
	ds_bpermute_b32 v161, v125, v109
	v_mov_b32_e32 v128, v127
	v_mov_b32_e32 v162, v126
	s_waitcnt lgkmcnt(0)
	v_pk_mul_f32 v[126:127], v[128:129], v[160:161]
	s_nop 0
	v_cndmask_b32_e64 v127, v127, -v127, s[36:37]
	v_cndmask_b32_e64 v126, v126, -v126, s[36:37]
	v_pk_fma_f32 v[108:109], v[108:109], v[162:163], v[126:127]
	ds_bpermute_b32 v126, v125, v110
	ds_bpermute_b32 v127, v125, v111
	v_mov_b32_e32 v129, v120
	v_mov_b32_e32 v120, v119
	v_mov_b32_e32 v128, v118
	s_waitcnt lgkmcnt(0)
	v_pk_mul_f32 v[118:119], v[120:121], v[126:127]
	s_nop 0
	v_cndmask_b32_e64 v119, v119, -v119, s[36:37]
	v_cndmask_b32_e64 v118, v118, -v118, s[36:37]
	v_pk_fma_f32 v[110:111], v[110:111], v[128:129], v[118:119]
	ds_bpermute_b32 v118, v125, v112
	ds_bpermute_b32 v119, v125, v113
	v_mov_b32_e32 v121, v116
	v_mov_b32_e32 v116, v115
	v_mov_b32_e32 v120, v114
	s_waitcnt lgkmcnt(0)
	v_pk_mul_f32 v[114:115], v[116:117], v[118:119]
	s_nop 0
	v_cndmask_b32_e64 v115, v115, -v115, s[36:37]
	v_cndmask_b32_e64 v114, v114, -v114, s[36:37]
	v_pk_fma_f32 v[112:113], v[112:113], v[120:121], v[114:115]

.LBB0_787:
	v_mov_b64_e32 v[112:113], v[104:105]
	s_and_b64 vcc, exec, s[40:41]
	v_mov_b64_e32 v[110:111], v[102:103]
	v_mov_b64_e32 v[108:109], v[100:101]
	v_mov_b64_e32 v[106:107], v[98:99]
	s_cbranch_vccnz .LBB0_789
	v_and_b32_e32 v106, 32, v167
	v_cmp_eq_u32_e32 vcc, 0, v106
	v_lshlrev_b32_e32 v107, 2, v0
	s_nop 0
	v_cndmask_b32_e32 v106, v120, v121, vcc
	v_cmp_lt_i32_e32 vcc, v198, v200
	v_lshl_or_b32 v106, v106, 7, v107
	s_nop 0
	v_cndmask_b32_e32 v107, v197, v198, vcc
	v_lshlrev_b32_e32 v115, 2, v107
	v_add_u32_e32 v106, s98, v106
	ds_read_b128 v[126:129], v106 offset:48
	ds_read_b128 v[110:113], v106 offset:32
	ds_read_b128 v[160:163], v106 offset:16
	s_nop 0
	ds_read_b128 v[106:109], v106
	ds_bpermute_b32 v116, v115, v98
	ds_bpermute_b32 v117, v115, v99
	s_waitcnt lgkmcnt(0)
	v_mov_b32_e32 v171, v108
	v_mov_b32_e32 v108, v107
	v_mov_b32_e32 v170, v106
	s_waitcnt lgkmcnt(0)
	v_pk_mul_f32 v[106:107], v[108:109], v[116:117]
	ds_bpermute_b32 v108, v115, v100
	ds_bpermute_b32 v109, v115, v101
	v_mov_b32_e32 v117, v162
	v_mov_b32_e32 v162, v161
	v_mov_b32_e32 v116, v160
	v_mov_b32_e32 v161, v112
	s_waitcnt lgkmcnt(0)
	v_pk_mul_f32 v[108:109], v[162:163], v[108:109]
	v_mov_b32_e32 v112, v111
	v_cndmask_b32_e64 v109, v109, -v109, s[38:39]
	v_cndmask_b32_e64 v108, v108, -v108, s[38:39]
	v_pk_fma_f32 v[108:109], v[100:101], v[116:117], v[108:109]
	ds_bpermute_b32 v116, v115, v102
	ds_bpermute_b32 v117, v115, v103
	v_mov_b32_e32 v160, v110
	v_cndmask_b32_e64 v107, v107, -v107, s[38:39]
	v_cndmask_b32_e64 v106, v106, -v106, s[38:39]
	v_pk_fma_f32 v[106:107], v[98:99], v[170:171], v[106:107]
	s_waitcnt lgkmcnt(0)
	v_pk_mul_f32 v[110:111], v[112:113], v[116:117]
	ds_bpermute_b32 v112, v115, v104
	ds_bpermute_b32 v113, v115, v105
	v_mov_b32_e32 v117, v128
	v_mov_b32_e32 v128, v127
	v_cndmask_b32_e64 v111, v111, -v111, s[38:39]
	v_cndmask_b32_e64 v110, v110, -v110, s[38:39]
	s_waitcnt lgkmcnt(0)
	v_pk_mul_f32 v[112:113], v[128:129], v[112:113]
	v_mov_b32_e32 v116, v126
	v_cndmask_b32_e64 v113, v113, -v113, s[38:39]
	v_cndmask_b32_e64 v112, v112, -v112, s[38:39]
	v_pk_fma_f32 v[110:111], v[102:103], v[160:161], v[110:111]
	v_pk_fma_f32 v[112:113], v[104:105], v[116:117], v[112:113]

.LBB0_790:
	s_mov_b64 s[10:11], 0
	v_cndmask_b32_e64 v115, v120, v121, s[38:39]
	v_lshlrev_b32_e32 v126, 4, v115
	s_cbranch_execz .LBB0_799
	s_and_b64 vcc, exec, s[40:41]
	s_cbranch_vccnz .LBB0_793
	v_and_b32_e32 v106, 32, v167
	v_cmp_eq_u32_e32 vcc, 0, v106
	v_lshlrev_b32_e32 v107, 2, v0
	s_nop 0
	v_cndmask_b32_e32 v106, v120, v121, vcc
	v_cmp_lt_i32_e32 vcc, v198, v200
	v_lshl_or_b32 v127, v106, 7, v107
	s_nop 0
	v_cndmask_b32_e32 v106, v197, v198, vcc
	v_lshlrev_b32_e32 v159, 2, v106
	v_add_u32_e32 v127, s98, v127
	ds_read_b128 v[106:109], v127 offset:48
	ds_read_b128 v[110:113], v127 offset:32
	ds_read_b128 v[114:117], v127 offset:16
	ds_read_b128 v[160:163], v127
	v_subrev_u32_e32 v127, s98, v127
	ds_bpermute_b32 v128, v159, v98
	ds_bpermute_b32 v129, v159, v99
	s_waitcnt lgkmcnt(0)
	v_mov_b32_e32 v171, v162
	v_mov_b32_e32 v162, v161
	s_waitcnt lgkmcnt(0)
	v_pk_mul_f32 v[128:129], v[162:163], v[128:129]
	v_mov_b32_e32 v170, v160
	v_cndmask_b32_e64 v129, v129, -v129, s[38:39]
	v_cndmask_b32_e64 v128, v128, -v128, s[38:39]
	v_pk_fma_f32 v[98:99], v[98:99], v[170:171], v[128:129]
	ds_bpermute_b32 v128, v159, v100
	ds_bpermute_b32 v129, v159, v101
	v_mov_b32_e32 v161, v116
	v_mov_b32_e32 v116, v115
	v_mov_b32_e32 v160, v114
	s_waitcnt lgkmcnt(0)
	v_pk_mul_f32 v[114:115], v[116:117], v[128:129]
	s_nop 0
	v_cndmask_b32_e64 v115, v115, -v115, s[38:39]
	v_cndmask_b32_e64 v114, v114, -v114, s[38:39]
	v_pk_fma_f32 v[100:101], v[100:101], v[160:161], v[114:115]
	ds_bpermute_b32 v114, v159, v102
	ds_bpermute_b32 v115, v159, v103
	v_mov_b32_e32 v117, v112
	v_mov_b32_e32 v112, v111
	v_mov_b32_e32 v116, v110
	s_waitcnt lgkmcnt(0)
	v_pk_mul_f32 v[110:111], v[112:113], v[114:115]
	s_nop 0
	v_cndmask_b32_e64 v111, v111, -v111, s[38:39]
	v_cndmask_b32_e64 v110, v110, -v110, s[38:39]
	v_pk_fma_f32 v[102:103], v[102:103], v[116:117], v[110:111]
	ds_bpermute_b32 v110, v159, v104
	ds_bpermute_b32 v111, v159, v105
	v_mov_b32_e32 v113, v108
	v_mov_b32_e32 v108, v107
	v_mov_b32_e32 v112, v106
	s_waitcnt lgkmcnt(0)
	v_pk_mul_f32 v[106:107], v[108:109], v[110:111]
	s_nop 0
	v_cndmask_b32_e64 v107, v107, -v107, s[38:39]
	v_cndmask_b32_e64 v106, v106, -v106, s[38:39]
	v_pk_fma_f32 v[104:105], v[104:105], v[112:113], v[106:107]
.LBB0_793:
	s_andn2_b64 vcc, exec, s[0:1]
	s_cbranch_vccnz .LBB0_796
	s_lshl_b32 s6, s91, 3
	v_readlane_b32 s7, v241, 60
	s_or_b32 s6, s6, s7
	s_mul_hi_i32 s7, s6, 0x55555556
	s_lshr_b32 vcc_lo, s7, 31
	s_add_i32 s7, s7, vcc_lo
	s_mul_i32 s7, s7, 3
	s_sub_i32 s6, s6, s7
	s_cmp_lg_u32 s6, 2
	s_cbranch_scc1 .LBB0_796
	v_xor_b32_e32 v106, 16, v197
	v_cmp_lt_i32_e32 vcc, v106, v200
	v_lshlrev_b32_e32 v127, 2, v126
	s_nop 0
	v_cndmask_b32_e32 v106, v197, v106, vcc
	v_lshlrev_b32_e32 v159, 2, v106
	v_add_u32_e32 v127, s99, v127
	ds_read_b128 v[106:109], v127 offset:48
	ds_read_b128 v[110:113], v127 offset:32
	ds_read_b128 v[114:117], v127 offset:16
	ds_read_b128 v[160:163], v127
	v_subrev_u32_e32 v127, s99, v127
	ds_bpermute_b32 v128, v159, v98
	ds_bpermute_b32 v129, v159, v99
	s_waitcnt lgkmcnt(0)
	v_mov_b32_e32 v171, v162
	v_mov_b32_e32 v162, v161
	s_waitcnt lgkmcnt(0)
	v_pk_mul_f32 v[128:129], v[162:163], v[128:129]
	v_mov_b32_e32 v170, v160
	v_cndmask_b32_e64 v129, v129, -v129, s[36:37]
	v_cndmask_b32_e64 v128, v128, -v128, s[36:37]
	v_pk_fma_f32 v[98:99], v[98:99], v[170:171], v[128:129]
	ds_bpermute_b32 v128, v159, v100
	ds_bpermute_b32 v129, v159, v101
	v_mov_b32_e32 v161, v116
	v_mov_b32_e32 v116, v115
	v_mov_b32_e32 v160, v114
	s_waitcnt lgkmcnt(0)
	v_pk_mul_f32 v[114:115], v[116:117], v[128:129]
	s_nop 0
	v_cndmask_b32_e64 v115, v115, -v115, s[36:37]
	v_cndmask_b32_e64 v114, v114, -v114, s[36:37]
	v_pk_fma_f32 v[100:101], v[100:101], v[160:161], v[114:115]
	ds_bpermute_b32 v114, v159, v102
	ds_bpermute_b32 v115, v159, v103
	v_mov_b32_e32 v117, v112
	v_mov_b32_e32 v112, v111
	v_mov_b32_e32 v116, v110
	s_waitcnt lgkmcnt(0)
	v_pk_mul_f32 v[110:111], v[112:113], v[114:115]
	s_nop 0
	v_cndmask_b32_e64 v111, v111, -v111, s[36:37]
	v_cndmask_b32_e64 v110, v110, -v110, s[36:37]
	v_pk_fma_f32 v[102:103], v[102:103], v[116:117], v[110:111]
	ds_bpermute_b32 v110, v159, v104
	ds_bpermute_b32 v111, v159, v105
	v_mov_b32_e32 v113, v108
	v_mov_b32_e32 v108, v107
	v_mov_b32_e32 v112, v106
	s_waitcnt lgkmcnt(0)
	v_pk_mul_f32 v[106:107], v[108:109], v[110:111]
	s_nop 0
	v_cndmask_b32_e64 v107, v107, -v107, s[36:37]
	v_cndmask_b32_e64 v106, v106, -v106, s[36:37]
	v_pk_fma_f32 v[104:105], v[104:105], v[112:113], v[106:107]

.LBB0_804:
	v_mov_b64_e32 v[104:105], v[96:97]
	s_and_b64 vcc, exec, s[40:41]
	v_mov_b64_e32 v[102:103], v[94:95]
	v_mov_b64_e32 v[100:101], v[92:93]
	v_mov_b64_e32 v[98:99], v[90:91]
	s_cbranch_vccnz .LBB0_806
	v_and_b32_e32 v98, 32, v167
	v_cmp_eq_u32_e32 vcc, 0, v98
	v_lshlrev_b32_e32 v99, 2, v0
	s_nop 0
	v_cndmask_b32_e32 v98, v120, v121, vcc
	v_cmp_lt_i32_e32 vcc, v198, v200
	v_lshl_or_b32 v98, v98, 7, v99
	s_nop 0
	v_cndmask_b32_e32 v99, v197, v198, vcc
	v_lshlrev_b32_e32 v107, 2, v99
	v_add_u32_e32 v98, s98, v98
	ds_read_b128 v[108:111], v98 offset:48
	ds_read_b128 v[102:105], v98 offset:32
	ds_read_b128 v[112:115], v98 offset:16
	s_nop 0
	ds_read_b128 v[98:101], v98
	ds_bpermute_b32 v116, v107, v90
	ds_bpermute_b32 v117, v107, v91
	s_waitcnt lgkmcnt(0)
	v_mov_b32_e32 v129, v100
	v_mov_b32_e32 v100, v99
	v_mov_b32_e32 v128, v98
	s_waitcnt lgkmcnt(0)
	v_pk_mul_f32 v[98:99], v[100:101], v[116:117]
	ds_bpermute_b32 v100, v107, v92
	ds_bpermute_b32 v101, v107, v93
	v_mov_b32_e32 v116, v112
	v_mov_b32_e32 v117, v114
	v_mov_b32_e32 v114, v113
	ds_bpermute_b32 v112, v107, v94
	ds_bpermute_b32 v113, v107, v95
	s_waitcnt lgkmcnt(2)
	v_pk_mul_f32 v[100:101], v[114:115], v[100:101]
	v_mov_b32_e32 v115, v104
	v_mov_b32_e32 v104, v103
	v_mov_b32_e32 v114, v102
	s_waitcnt lgkmcnt(0)
	v_pk_mul_f32 v[102:103], v[104:105], v[112:113]
	ds_bpermute_b32 v104, v107, v96
	ds_bpermute_b32 v105, v107, v97
	v_mov_b32_e32 v113, v110
	v_mov_b32_e32 v110, v109
	v_cndmask_b32_e64 v99, v99, -v99, s[38:39]
	v_cndmask_b32_e64 v98, v98, -v98, s[38:39]
	s_waitcnt lgkmcnt(0)
	v_pk_mul_f32 v[104:105], v[110:111], v[104:105]
	v_cndmask_b32_e64 v101, v101, -v101, s[38:39]
	v_cndmask_b32_e64 v100, v100, -v100, s[38:39]
	v_cndmask_b32_e64 v103, v103, -v103, s[38:39]
	v_cndmask_b32_e64 v102, v102, -v102, s[38:39]
	v_mov_b32_e32 v112, v108
	v_cndmask_b32_e64 v105, v105, -v105, s[38:39]
	v_cndmask_b32_e64 v104, v104, -v104, s[38:39]
	v_pk_fma_f32 v[98:99], v[90:91], v[128:129], v[98:99]
	v_pk_fma_f32 v[100:101], v[92:93], v[116:117], v[100:101]
	v_pk_fma_f32 v[102:103], v[94:95], v[114:115], v[102:103]
	v_pk_fma_f32 v[104:105], v[96:97], v[112:113], v[104:105]

.LBB0_807:
	s_mov_b64 s[10:11], 0
	s_cbranch_execz .LBB0_816
	s_and_b64 vcc, exec, s[40:41]
	s_cbranch_vccnz .LBB0_810
	v_and_b32_e32 v98, 32, v167
	v_cmp_eq_u32_e32 vcc, 0, v98
	v_lshlrev_b32_e32 v99, 2, v0
	s_nop 0
	v_cndmask_b32_e32 v98, v120, v121, vcc
	v_cmp_lt_i32_e32 vcc, v198, v200
	v_lshl_or_b32 v110, v98, 7, v99
	s_nop 0
	v_cndmask_b32_e32 v98, v197, v198, vcc
	v_lshlrev_b32_e32 v120, 2, v98
	v_add_u32_e32 v110, s98, v110
	ds_read_b128 v[98:101], v110 offset:48
	ds_read_b128 v[102:105], v110 offset:32
	ds_read_b128 v[106:109], v110 offset:16
	s_nop 0
	ds_read_b128 v[110:113], v110
	ds_bpermute_b32 v114, v120, v90
	ds_bpermute_b32 v115, v120, v91
	s_waitcnt lgkmcnt(0)
	v_mov_b32_e32 v117, v112
	v_mov_b32_e32 v112, v111
	v_mov_b32_e32 v116, v110
	s_waitcnt lgkmcnt(0)
	v_pk_mul_f32 v[110:111], v[112:113], v[114:115]
	v_mov_b32_e32 v113, v108
	v_cndmask_b32_e64 v111, v111, -v111, s[38:39]
	v_cndmask_b32_e64 v110, v110, -v110, s[38:39]
	v_pk_fma_f32 v[90:91], v[90:91], v[116:117], v[110:111]
	ds_bpermute_b32 v110, v120, v92
	ds_bpermute_b32 v111, v120, v93
	v_mov_b32_e32 v108, v107
	v_mov_b32_e32 v112, v106
	s_waitcnt lgkmcnt(0)
	v_pk_mul_f32 v[106:107], v[108:109], v[110:111]
	s_nop 0
	v_cndmask_b32_e64 v107, v107, -v107, s[38:39]
	v_cndmask_b32_e64 v106, v106, -v106, s[38:39]
	v_pk_fma_f32 v[92:93], v[92:93], v[112:113], v[106:107]
	ds_bpermute_b32 v106, v120, v94
	ds_bpermute_b32 v107, v120, v95
	v_mov_b32_e32 v109, v104
	v_mov_b32_e32 v104, v103
	v_mov_b32_e32 v108, v102
	s_waitcnt lgkmcnt(0)
	v_pk_mul_f32 v[102:103], v[104:105], v[106:107]
	s_nop 0
	v_cndmask_b32_e64 v103, v103, -v103, s[38:39]
	v_cndmask_b32_e64 v102, v102, -v102, s[38:39]
	v_pk_fma_f32 v[94:95], v[94:95], v[108:109], v[102:103]
	ds_bpermute_b32 v102, v120, v96
	ds_bpermute_b32 v103, v120, v97
	v_mov_b32_e32 v105, v100
	v_mov_b32_e32 v100, v99
	v_mov_b32_e32 v104, v98
	s_waitcnt lgkmcnt(0)
	v_pk_mul_f32 v[98:99], v[100:101], v[102:103]
	s_nop 0
	v_cndmask_b32_e64 v99, v99, -v99, s[38:39]
	v_cndmask_b32_e64 v98, v98, -v98, s[38:39]
	v_pk_fma_f32 v[96:97], v[96:97], v[104:105], v[98:99]
.LBB0_810:
	s_andn2_b64 vcc, exec, s[0:1]
	s_cbranch_vccnz .LBB0_813
	s_lshl_b32 s6, s91, 3
	v_readlane_b32 s7, v241, 61
	s_or_b32 s6, s6, s7
	s_mul_hi_i32 s7, s6, 0x55555556
	s_lshr_b32 vcc_lo, s7, 31
	s_add_i32 s7, s7, vcc_lo
	s_mul_i32 s7, s7, 3
	s_sub_i32 s6, s6, s7
	s_cmp_lg_u32 s6, 2
	s_cbranch_scc1 .LBB0_813
	v_xor_b32_e32 v98, 16, v197
	v_cmp_lt_i32_e32 vcc, v98, v200
	v_lshlrev_b32_e32 v110, 2, v126
	s_nop 0
	v_cndmask_b32_e32 v98, v197, v98, vcc
	v_lshlrev_b32_e32 v120, 2, v98
	v_add_u32_e32 v110, s99, v110
	ds_read_b128 v[98:101], v110 offset:48
	ds_read_b128 v[102:105], v110 offset:32
	ds_read_b128 v[106:109], v110 offset:16
	s_nop 0
	ds_read_b128 v[110:113], v110
	ds_bpermute_b32 v114, v120, v90
	ds_bpermute_b32 v115, v120, v91
	s_waitcnt lgkmcnt(0)
	v_mov_b32_e32 v117, v112
	v_mov_b32_e32 v112, v111
	v_mov_b32_e32 v116, v110
	s_waitcnt lgkmcnt(0)
	v_pk_mul_f32 v[110:111], v[112:113], v[114:115]
	v_mov_b32_e32 v113, v108
	v_cndmask_b32_e64 v111, v111, -v111, s[36:37]
	v_cndmask_b32_e64 v110, v110, -v110, s[36:37]
	v_pk_fma_f32 v[90:91], v[90:91], v[116:117], v[110:111]
	ds_bpermute_b32 v110, v120, v92
	ds_bpermute_b32 v111, v120, v93
	v_mov_b32_e32 v108, v107
	v_mov_b32_e32 v112, v106
	s_waitcnt lgkmcnt(0)
	v_pk_mul_f32 v[106:107], v[108:109], v[110:111]
	s_nop 0
	v_cndmask_b32_e64 v107, v107, -v107, s[36:37]
	v_cndmask_b32_e64 v106, v106, -v106, s[36:37]
	v_pk_fma_f32 v[92:93], v[92:93], v[112:113], v[106:107]
	ds_bpermute_b32 v106, v120, v94
	ds_bpermute_b32 v107, v120, v95
	v_mov_b32_e32 v109, v104
	v_mov_b32_e32 v104, v103
	v_mov_b32_e32 v108, v102
	s_waitcnt lgkmcnt(0)
	v_pk_mul_f32 v[102:103], v[104:105], v[106:107]
	s_nop 0
	v_cndmask_b32_e64 v103, v103, -v103, s[36:37]
	v_cndmask_b32_e64 v102, v102, -v102, s[36:37]
	v_pk_fma_f32 v[94:95], v[94:95], v[108:109], v[102:103]
	ds_bpermute_b32 v102, v120, v96
	ds_bpermute_b32 v103, v120, v97
	v_mov_b32_e32 v105, v100
	v_mov_b32_e32 v100, v99
	v_mov_b32_e32 v104, v98
	s_waitcnt lgkmcnt(0)
	v_pk_mul_f32 v[98:99], v[100:101], v[102:103]
	s_nop 0
	v_cndmask_b32_e64 v99, v99, -v99, s[36:37]
	v_cndmask_b32_e64 v98, v98, -v98, s[36:37]
	v_pk_fma_f32 v[96:97], v[96:97], v[104:105], v[98:99]

.LBB0_823:
	v_mov_b64_e32 v[96:97], v[88:89]
	s_and_b64 vcc, exec, s[40:41]
	v_mov_b64_e32 v[94:95], v[86:87]
	v_mov_b64_e32 v[92:93], v[84:85]
	v_mov_b64_e32 v[90:91], v[82:83]
	s_cbranch_vccnz .LBB0_825
	v_and_b32_e32 v90, 32, v167
	v_cmp_eq_u32_e32 vcc, 0, v90
	v_lshlrev_b32_e32 v91, 2, v0
	s_nop 0
	v_cndmask_b32_e32 v90, v104, v105, vcc
	v_cmp_lt_i32_e32 vcc, v198, v200
	v_lshl_or_b32 v90, v90, 7, v91
	s_nop 0
	v_cndmask_b32_e32 v91, v197, v198, vcc
	v_lshlrev_b32_e32 v99, 2, v91
	v_add_u32_e32 v90, s98, v90
	ds_read_b128 v[108:111], v90 offset:48
	ds_read_b128 v[94:97], v90 offset:32
	ds_read_b128 v[112:115], v90 offset:16
	s_nop 0
	ds_read_b128 v[90:93], v90
	ds_bpermute_b32 v100, v99, v82
	ds_bpermute_b32 v101, v99, v83
	s_waitcnt lgkmcnt(0)
	v_mov_b32_e32 v117, v92
	v_mov_b32_e32 v92, v91
	v_mov_b32_e32 v116, v90
	s_waitcnt lgkmcnt(0)
	v_pk_mul_f32 v[90:91], v[92:93], v[100:101]
	ds_bpermute_b32 v92, v99, v84
	ds_bpermute_b32 v93, v99, v85
	v_mov_b32_e32 v101, v114
	v_mov_b32_e32 v114, v113
	v_mov_b32_e32 v100, v112
	v_mov_b32_e32 v113, v96
	s_waitcnt lgkmcnt(0)
	v_pk_mul_f32 v[92:93], v[114:115], v[92:93]
	v_mov_b32_e32 v96, v95
	v_cndmask_b32_e64 v93, v93, -v93, s[38:39]
	v_cndmask_b32_e64 v92, v92, -v92, s[38:39]
	v_pk_fma_f32 v[92:93], v[84:85], v[100:101], v[92:93]
	ds_bpermute_b32 v100, v99, v86
	ds_bpermute_b32 v101, v99, v87
	v_mov_b32_e32 v112, v94
	v_cndmask_b32_e64 v91, v91, -v91, s[38:39]
	v_cndmask_b32_e64 v90, v90, -v90, s[38:39]
	v_pk_fma_f32 v[90:91], v[82:83], v[116:117], v[90:91]
	s_waitcnt lgkmcnt(0)
	v_pk_mul_f32 v[94:95], v[96:97], v[100:101]
	ds_bpermute_b32 v96, v99, v88
	ds_bpermute_b32 v97, v99, v89
	v_mov_b32_e32 v101, v110
	v_mov_b32_e32 v110, v109
	v_cndmask_b32_e64 v95, v95, -v95, s[38:39]
	v_cndmask_b32_e64 v94, v94, -v94, s[38:39]
	s_waitcnt lgkmcnt(0)
	v_pk_mul_f32 v[96:97], v[110:111], v[96:97]
	v_mov_b32_e32 v100, v108
	v_cndmask_b32_e64 v97, v97, -v97, s[38:39]
	v_cndmask_b32_e64 v96, v96, -v96, s[38:39]
	v_pk_fma_f32 v[94:95], v[86:87], v[112:113], v[94:95]
	v_pk_fma_f32 v[96:97], v[88:89], v[100:101], v[96:97]

.LBB0_826:
	s_mov_b64 s[10:11], 0
	v_cndmask_b32_e64 v99, v104, v105, s[38:39]
	v_lshlrev_b32_e32 v108, 4, v99
	s_cbranch_execz .LBB0_835
	s_and_b64 vcc, exec, s[40:41]
	s_cbranch_vccnz .LBB0_829
	v_and_b32_e32 v90, 32, v167
	v_cmp_eq_u32_e32 vcc, 0, v90
	v_lshlrev_b32_e32 v91, 2, v0
	s_nop 0
	v_cndmask_b32_e32 v90, v104, v105, vcc
	v_cmp_lt_i32_e32 vcc, v198, v200
	v_lshl_or_b32 v109, v90, 7, v91
	s_nop 0
	v_cndmask_b32_e32 v90, v197, v198, vcc
	v_lshlrev_b32_e32 v118, 2, v90
	v_add_u32_e32 v109, s98, v109
	ds_read_b128 v[90:93], v109 offset:48
	ds_read_b128 v[94:97], v109 offset:32
	ds_read_b128 v[98:101], v109 offset:16
	ds_read_b128 v[110:113], v109
	v_subrev_u32_e32 v109, s98, v109
	ds_bpermute_b32 v114, v118, v82
	ds_bpermute_b32 v115, v118, v83
	s_waitcnt lgkmcnt(0)
	v_mov_b32_e32 v117, v112
	v_mov_b32_e32 v112, v111
	v_mov_b32_e32 v116, v110
	s_waitcnt lgkmcnt(0)
	v_pk_mul_f32 v[110:111], v[112:113], v[114:115]
	v_mov_b32_e32 v113, v100
	v_cndmask_b32_e64 v111, v111, -v111, s[38:39]
	v_cndmask_b32_e64 v110, v110, -v110, s[38:39]
	v_pk_fma_f32 v[82:83], v[82:83], v[116:117], v[110:111]
	ds_bpermute_b32 v110, v118, v84
	ds_bpermute_b32 v111, v118, v85
	v_mov_b32_e32 v100, v99
	v_mov_b32_e32 v112, v98
	s_waitcnt lgkmcnt(0)
	v_pk_mul_f32 v[98:99], v[100:101], v[110:111]
	s_nop 0
	v_cndmask_b32_e64 v99, v99, -v99, s[38:39]
	v_cndmask_b32_e64 v98, v98, -v98, s[38:39]
	v_pk_fma_f32 v[84:85], v[84:85], v[112:113], v[98:99]
	ds_bpermute_b32 v98, v118, v86
	ds_bpermute_b32 v99, v118, v87
	v_mov_b32_e32 v101, v96
	v_mov_b32_e32 v96, v95
	v_mov_b32_e32 v100, v94
	s_waitcnt lgkmcnt(0)
	v_pk_mul_f32 v[94:95], v[96:97], v[98:99]
	s_nop 0
	v_cndmask_b32_e64 v95, v95, -v95, s[38:39]
	v_cndmask_b32_e64 v94, v94, -v94, s[38:39]
	v_pk_fma_f32 v[86:87], v[86:87], v[100:101], v[94:95]
	ds_bpermute_b32 v94, v118, v88
	ds_bpermute_b32 v95, v118, v89
	v_mov_b32_e32 v97, v92
	v_mov_b32_e32 v92, v91
	v_mov_b32_e32 v96, v90
	s_waitcnt lgkmcnt(0)
	v_pk_mul_f32 v[90:91], v[92:93], v[94:95]
	s_nop 0
	v_cndmask_b32_e64 v91, v91, -v91, s[38:39]
	v_cndmask_b32_e64 v90, v90, -v90, s[38:39]
	v_pk_fma_f32 v[88:89], v[88:89], v[96:97], v[90:91]
.LBB0_829:
	s_andn2_b64 vcc, exec, s[0:1]
	s_cbranch_vccnz .LBB0_832
	s_lshl_b32 s6, s91, 3
	v_readlane_b32 s7, v241, 60
	s_or_b32 s6, s6, s7
	s_mul_hi_i32 s7, s6, 0x55555556
	s_lshr_b32 vcc_lo, s7, 31
	s_add_i32 s7, s7, vcc_lo
	s_mul_i32 s7, s7, 3
	s_sub_i32 s6, s6, s7
	s_cmp_lg_u32 s6, 2
	s_cbranch_scc1 .LBB0_832
	v_xor_b32_e32 v90, 16, v197
	v_cmp_lt_i32_e32 vcc, v90, v200
	v_lshlrev_b32_e32 v109, 2, v108
	s_nop 0
	v_cndmask_b32_e32 v90, v197, v90, vcc
	v_lshlrev_b32_e32 v118, 2, v90
	v_add_u32_e32 v109, s99, v109
	ds_read_b128 v[90:93], v109 offset:48
	ds_read_b128 v[94:97], v109 offset:32
	ds_read_b128 v[98:101], v109 offset:16
	ds_read_b128 v[110:113], v109
	v_subrev_u32_e32 v109, s99, v109
	ds_bpermute_b32 v114, v118, v82
	ds_bpermute_b32 v115, v118, v83
	s_waitcnt lgkmcnt(0)
	v_mov_b32_e32 v117, v112
	v_mov_b32_e32 v112, v111
	v_mov_b32_e32 v116, v110
	s_waitcnt lgkmcnt(0)
	v_pk_mul_f32 v[110:111], v[112:113], v[114:115]
	v_mov_b32_e32 v113, v100
	v_cndmask_b32_e64 v111, v111, -v111, s[36:37]
	v_cndmask_b32_e64 v110, v110, -v110, s[36:37]
	v_pk_fma_f32 v[82:83], v[82:83], v[116:117], v[110:111]
	ds_bpermute_b32 v110, v118, v84
	ds_bpermute_b32 v111, v118, v85
	v_mov_b32_e32 v100, v99
	v_mov_b32_e32 v112, v98
	s_waitcnt lgkmcnt(0)
	v_pk_mul_f32 v[98:99], v[100:101], v[110:111]
	s_nop 0
	v_cndmask_b32_e64 v99, v99, -v99, s[36:37]
	v_cndmask_b32_e64 v98, v98, -v98, s[36:37]
	v_pk_fma_f32 v[84:85], v[84:85], v[112:113], v[98:99]
	ds_bpermute_b32 v98, v118, v86
	ds_bpermute_b32 v99, v118, v87
	v_mov_b32_e32 v101, v96
	v_mov_b32_e32 v96, v95
	v_mov_b32_e32 v100, v94
	s_waitcnt lgkmcnt(0)
	v_pk_mul_f32 v[94:95], v[96:97], v[98:99]
	s_nop 0
	v_cndmask_b32_e64 v95, v95, -v95, s[36:37]
	v_cndmask_b32_e64 v94, v94, -v94, s[36:37]
	v_pk_fma_f32 v[86:87], v[86:87], v[100:101], v[94:95]
	ds_bpermute_b32 v94, v118, v88
	ds_bpermute_b32 v95, v118, v89
	v_mov_b32_e32 v97, v92
	v_mov_b32_e32 v92, v91
	v_mov_b32_e32 v96, v90
	s_waitcnt lgkmcnt(0)
	v_pk_mul_f32 v[90:91], v[92:93], v[94:95]
	s_nop 0
	v_cndmask_b32_e64 v91, v91, -v91, s[36:37]
	v_cndmask_b32_e64 v90, v90, -v90, s[36:37]
	v_pk_fma_f32 v[88:89], v[88:89], v[96:97], v[90:91]

.LBB0_840:
	v_mov_b64_e32 v[88:89], v[80:81]
	s_and_b64 vcc, exec, s[40:41]
	v_mov_b64_e32 v[86:87], v[78:79]
	v_mov_b64_e32 v[84:85], v[76:77]
	v_mov_b64_e32 v[82:83], v[74:75]
	s_cbranch_vccnz .LBB0_842
	v_and_b32_e32 v82, 32, v167
	v_cmp_eq_u32_e32 vcc, 0, v82
	v_lshlrev_b32_e32 v83, 2, v0
	s_nop 0
	v_cndmask_b32_e32 v82, v104, v105, vcc
	v_cmp_lt_i32_e32 vcc, v198, v200
	v_lshl_or_b32 v82, v82, 7, v83
	s_nop 0
	v_cndmask_b32_e32 v83, v197, v198, vcc
	v_lshlrev_b32_e32 v91, 2, v83
	v_add_u32_e32 v82, s98, v82
	ds_read_b128 v[92:95], v82 offset:48
	ds_read_b128 v[86:89], v82 offset:32
	ds_read_b128 v[96:99], v82 offset:16
	s_nop 0
	ds_read_b128 v[82:85], v82
	ds_bpermute_b32 v100, v91, v74
	ds_bpermute_b32 v101, v91, v75
	s_waitcnt lgkmcnt(0)
	v_mov_b32_e32 v111, v84
	v_mov_b32_e32 v84, v83
	v_mov_b32_e32 v110, v82
	s_waitcnt lgkmcnt(0)
	v_pk_mul_f32 v[82:83], v[84:85], v[100:101]
	ds_bpermute_b32 v84, v91, v76
	ds_bpermute_b32 v85, v91, v77
	v_mov_b32_e32 v100, v96
	v_mov_b32_e32 v101, v98
	v_mov_b32_e32 v98, v97
	ds_bpermute_b32 v96, v91, v78
	ds_bpermute_b32 v97, v91, v79
	s_waitcnt lgkmcnt(2)
	v_pk_mul_f32 v[84:85], v[98:99], v[84:85]
	v_mov_b32_e32 v99, v88
	v_mov_b32_e32 v88, v87
	v_mov_b32_e32 v98, v86
	s_waitcnt lgkmcnt(0)
	v_pk_mul_f32 v[86:87], v[88:89], v[96:97]
	ds_bpermute_b32 v88, v91, v80
	ds_bpermute_b32 v89, v91, v81
	v_mov_b32_e32 v97, v94
	v_mov_b32_e32 v94, v93
	v_cndmask_b32_e64 v83, v83, -v83, s[38:39]
	v_cndmask_b32_e64 v82, v82, -v82, s[38:39]
	s_waitcnt lgkmcnt(0)
	v_pk_mul_f32 v[88:89], v[94:95], v[88:89]
	v_cndmask_b32_e64 v85, v85, -v85, s[38:39]
	v_cndmask_b32_e64 v84, v84, -v84, s[38:39]
	v_cndmask_b32_e64 v87, v87, -v87, s[38:39]
	v_cndmask_b32_e64 v86, v86, -v86, s[38:39]
	v_mov_b32_e32 v96, v92
	v_cndmask_b32_e64 v89, v89, -v89, s[38:39]
	v_cndmask_b32_e64 v88, v88, -v88, s[38:39]
	v_pk_fma_f32 v[82:83], v[74:75], v[110:111], v[82:83]
	v_pk_fma_f32 v[84:85], v[76:77], v[100:101], v[84:85]
	v_pk_fma_f32 v[86:87], v[78:79], v[98:99], v[86:87]
	v_pk_fma_f32 v[88:89], v[80:81], v[96:97], v[88:89]

.LBB0_843:
	s_mov_b64 s[10:11], 0
	s_cbranch_execz .LBB0_852
	s_and_b64 vcc, exec, s[40:41]
	s_cbranch_vccnz .LBB0_846
	v_and_b32_e32 v82, 32, v167
	v_cmp_eq_u32_e32 vcc, 0, v82
	v_lshlrev_b32_e32 v83, 2, v0
	s_nop 0
	v_cndmask_b32_e32 v82, v104, v105, vcc
	v_cmp_lt_i32_e32 vcc, v198, v200
	v_lshl_or_b32 v94, v82, 7, v83
	s_nop 0
	v_cndmask_b32_e32 v82, v197, v198, vcc
	v_lshlrev_b32_e32 v104, 2, v82
	v_add_u32_e32 v94, s98, v94
	ds_read_b128 v[82:85], v94 offset:48
	ds_read_b128 v[86:89], v94 offset:32
	ds_read_b128 v[90:93], v94 offset:16
	s_nop 0
	ds_read_b128 v[94:97], v94
	ds_bpermute_b32 v98, v104, v74
	ds_bpermute_b32 v99, v104, v75
	s_waitcnt lgkmcnt(0)
	v_mov_b32_e32 v101, v96
	v_mov_b32_e32 v96, v95
	v_mov_b32_e32 v100, v94
	s_waitcnt lgkmcnt(0)
	v_pk_mul_f32 v[94:95], v[96:97], v[98:99]
	v_mov_b32_e32 v97, v92
	v_cndmask_b32_e64 v95, v95, -v95, s[38:39]
	v_cndmask_b32_e64 v94, v94, -v94, s[38:39]
	v_pk_fma_f32 v[74:75], v[74:75], v[100:101], v[94:95]
	ds_bpermute_b32 v94, v104, v76
	ds_bpermute_b32 v95, v104, v77
	v_mov_b32_e32 v92, v91
	v_mov_b32_e32 v96, v90
	s_waitcnt lgkmcnt(0)
	v_pk_mul_f32 v[90:91], v[92:93], v[94:95]
	s_nop 0
	v_cndmask_b32_e64 v91, v91, -v91, s[38:39]
	v_cndmask_b32_e64 v90, v90, -v90, s[38:39]
	v_pk_fma_f32 v[76:77], v[76:77], v[96:97], v[90:91]
	ds_bpermute_b32 v90, v104, v78
	ds_bpermute_b32 v91, v104, v79
	v_mov_b32_e32 v93, v88
	v_mov_b32_e32 v88, v87
	v_mov_b32_e32 v92, v86
	s_waitcnt lgkmcnt(0)
	v_pk_mul_f32 v[86:87], v[88:89], v[90:91]
	s_nop 0
	v_cndmask_b32_e64 v87, v87, -v87, s[38:39]
	v_cndmask_b32_e64 v86, v86, -v86, s[38:39]
	v_pk_fma_f32 v[78:79], v[78:79], v[92:93], v[86:87]
	ds_bpermute_b32 v86, v104, v80
	ds_bpermute_b32 v87, v104, v81
	v_mov_b32_e32 v89, v84
	v_mov_b32_e32 v84, v83
	v_mov_b32_e32 v88, v82
	s_waitcnt lgkmcnt(0)
	v_pk_mul_f32 v[82:83], v[84:85], v[86:87]
	s_nop 0
	v_cndmask_b32_e64 v83, v83, -v83, s[38:39]
	v_cndmask_b32_e64 v82, v82, -v82, s[38:39]
	v_pk_fma_f32 v[80:81], v[80:81], v[88:89], v[82:83]
.LBB0_846:
	s_andn2_b64 vcc, exec, s[0:1]
	s_cbranch_vccnz .LBB0_849
	s_lshl_b32 s6, s91, 3
	v_readlane_b32 s7, v241, 61
	s_or_b32 s6, s6, s7
	s_mul_hi_i32 s7, s6, 0x55555556
	s_lshr_b32 vcc_lo, s7, 31
	s_add_i32 s7, s7, vcc_lo
	s_mul_i32 s7, s7, 3
	s_sub_i32 s6, s6, s7
	s_cmp_lg_u32 s6, 2
	s_cbranch_scc1 .LBB0_849
	v_xor_b32_e32 v82, 16, v197
	v_cmp_lt_i32_e32 vcc, v82, v200
	v_lshlrev_b32_e32 v94, 2, v108
	s_nop 0
	v_cndmask_b32_e32 v82, v197, v82, vcc
	v_lshlrev_b32_e32 v104, 2, v82
	v_add_u32_e32 v94, s99, v94
	ds_read_b128 v[82:85], v94 offset:48
	ds_read_b128 v[86:89], v94 offset:32
	ds_read_b128 v[90:93], v94 offset:16
	s_nop 0
	ds_read_b128 v[94:97], v94
	ds_bpermute_b32 v98, v104, v74
	ds_bpermute_b32 v99, v104, v75
	s_waitcnt lgkmcnt(0)
	v_mov_b32_e32 v101, v96
	v_mov_b32_e32 v96, v95
	v_mov_b32_e32 v100, v94
	s_waitcnt lgkmcnt(0)
	v_pk_mul_f32 v[94:95], v[96:97], v[98:99]
	v_mov_b32_e32 v97, v92
	v_cndmask_b32_e64 v95, v95, -v95, s[36:37]
	v_cndmask_b32_e64 v94, v94, -v94, s[36:37]
	v_pk_fma_f32 v[74:75], v[74:75], v[100:101], v[94:95]
	ds_bpermute_b32 v94, v104, v76
	ds_bpermute_b32 v95, v104, v77
	v_mov_b32_e32 v92, v91
	v_mov_b32_e32 v96, v90
	s_waitcnt lgkmcnt(0)
	v_pk_mul_f32 v[90:91], v[92:93], v[94:95]
	s_nop 0
	v_cndmask_b32_e64 v91, v91, -v91, s[36:37]
	v_cndmask_b32_e64 v90, v90, -v90, s[36:37]
	v_pk_fma_f32 v[76:77], v[76:77], v[96:97], v[90:91]
	ds_bpermute_b32 v90, v104, v78
	ds_bpermute_b32 v91, v104, v79
	v_mov_b32_e32 v93, v88
	v_mov_b32_e32 v88, v87
	v_mov_b32_e32 v92, v86
	s_waitcnt lgkmcnt(0)
	v_pk_mul_f32 v[86:87], v[88:89], v[90:91]
	s_nop 0
	v_cndmask_b32_e64 v87, v87, -v87, s[36:37]
	v_cndmask_b32_e64 v86, v86, -v86, s[36:37]
	v_pk_fma_f32 v[78:79], v[78:79], v[92:93], v[86:87]
	ds_bpermute_b32 v86, v104, v80
	ds_bpermute_b32 v87, v104, v81
	v_mov_b32_e32 v89, v84
	v_mov_b32_e32 v84, v83
	v_mov_b32_e32 v88, v82
	s_waitcnt lgkmcnt(0)
	v_pk_mul_f32 v[82:83], v[84:85], v[86:87]
	s_nop 0
	v_cndmask_b32_e64 v83, v83, -v83, s[36:37]
	v_cndmask_b32_e64 v82, v82, -v82, s[36:37]
	v_pk_fma_f32 v[80:81], v[80:81], v[88:89], v[82:83]

.LBB0_859:
	v_mov_b64_e32 v[80:81], v[72:73]
	s_and_b64 vcc, exec, s[40:41]
	v_mov_b64_e32 v[78:79], v[70:71]
	v_mov_b64_e32 v[76:77], v[68:69]
	v_mov_b64_e32 v[74:75], v[66:67]
	s_cbranch_vccnz .LBB0_861
	v_and_b32_e32 v74, 32, v167
	v_cmp_eq_u32_e32 vcc, 0, v74
	v_lshlrev_b32_e32 v75, 2, v0
	s_nop 0
	v_cndmask_b32_e32 v74, v88, v89, vcc
	v_cmp_lt_i32_e32 vcc, v198, v200
	v_lshl_or_b32 v74, v74, 7, v75
	s_nop 0
	v_cndmask_b32_e32 v75, v197, v198, vcc
	v_lshlrev_b32_e32 v83, 2, v75
	v_add_u32_e32 v74, s98, v74
	ds_read_b128 v[92:95], v74 offset:48
	ds_read_b128 v[78:81], v74 offset:32
	ds_read_b128 v[96:99], v74 offset:16
	s_nop 0
	ds_read_b128 v[74:77], v74
	ds_bpermute_b32 v84, v83, v66
	ds_bpermute_b32 v85, v83, v67
	s_waitcnt lgkmcnt(0)
	v_mov_b32_e32 v101, v76
	v_mov_b32_e32 v76, v75
	v_mov_b32_e32 v100, v74
	s_waitcnt lgkmcnt(0)
	v_pk_mul_f32 v[74:75], v[76:77], v[84:85]
	ds_bpermute_b32 v76, v83, v68
	ds_bpermute_b32 v77, v83, v69
	v_mov_b32_e32 v85, v98
	v_mov_b32_e32 v98, v97
	v_mov_b32_e32 v84, v96
	v_mov_b32_e32 v97, v80
	s_waitcnt lgkmcnt(0)
	v_pk_mul_f32 v[76:77], v[98:99], v[76:77]
	v_mov_b32_e32 v80, v79
	v_cndmask_b32_e64 v77, v77, -v77, s[38:39]
	v_cndmask_b32_e64 v76, v76, -v76, s[38:39]
	v_pk_fma_f32 v[76:77], v[68:69], v[84:85], v[76:77]
	ds_bpermute_b32 v84, v83, v70
	ds_bpermute_b32 v85, v83, v71
	v_mov_b32_e32 v96, v78
	v_cndmask_b32_e64 v75, v75, -v75, s[38:39]
	v_cndmask_b32_e64 v74, v74, -v74, s[38:39]
	v_pk_fma_f32 v[74:75], v[66:67], v[100:101], v[74:75]
	s_waitcnt lgkmcnt(0)
	v_pk_mul_f32 v[78:79], v[80:81], v[84:85]
	ds_bpermute_b32 v80, v83, v72
	ds_bpermute_b32 v81, v83, v73
	v_mov_b32_e32 v85, v94
	v_mov_b32_e32 v94, v93
	v_cndmask_b32_e64 v79, v79, -v79, s[38:39]
	v_cndmask_b32_e64 v78, v78, -v78, s[38:39]
	s_waitcnt lgkmcnt(0)
	v_pk_mul_f32 v[80:81], v[94:95], v[80:81]
	v_mov_b32_e32 v84, v92
	v_cndmask_b32_e64 v81, v81, -v81, s[38:39]
	v_cndmask_b32_e64 v80, v80, -v80, s[38:39]
	v_pk_fma_f32 v[78:79], v[70:71], v[96:97], v[78:79]
	v_pk_fma_f32 v[80:81], v[72:73], v[84:85], v[80:81]

.LBB0_862:
	s_mov_b64 s[10:11], 0
	v_cndmask_b32_e64 v83, v88, v89, s[38:39]
	v_lshlrev_b32_e32 v92, 4, v83
	s_cbranch_execz .LBB0_871
	s_and_b64 vcc, exec, s[40:41]
	s_cbranch_vccnz .LBB0_865
	v_and_b32_e32 v74, 32, v167
	v_cmp_eq_u32_e32 vcc, 0, v74
	v_lshlrev_b32_e32 v75, 2, v0
	s_nop 0
	v_cndmask_b32_e32 v74, v88, v89, vcc
	v_cmp_lt_i32_e32 vcc, v198, v200
	v_lshl_or_b32 v93, v74, 7, v75
	s_nop 0
	v_cndmask_b32_e32 v74, v197, v198, vcc
	v_lshlrev_b32_e32 v102, 2, v74
	v_add_u32_e32 v93, s98, v93
	ds_read_b128 v[74:77], v93 offset:48
	ds_read_b128 v[78:81], v93 offset:32
	ds_read_b128 v[82:85], v93 offset:16
	ds_read_b128 v[94:97], v93
	v_subrev_u32_e32 v93, s98, v93
	ds_bpermute_b32 v98, v102, v66
	ds_bpermute_b32 v99, v102, v67
	s_waitcnt lgkmcnt(0)
	v_mov_b32_e32 v101, v96
	v_mov_b32_e32 v96, v95
	v_mov_b32_e32 v100, v94
	s_waitcnt lgkmcnt(0)
	v_pk_mul_f32 v[94:95], v[96:97], v[98:99]
	v_mov_b32_e32 v97, v84
	v_cndmask_b32_e64 v95, v95, -v95, s[38:39]
	v_cndmask_b32_e64 v94, v94, -v94, s[38:39]
	v_pk_fma_f32 v[66:67], v[66:67], v[100:101], v[94:95]
	ds_bpermute_b32 v94, v102, v68
	ds_bpermute_b32 v95, v102, v69
	v_mov_b32_e32 v84, v83
	v_mov_b32_e32 v96, v82
	s_waitcnt lgkmcnt(0)
	v_pk_mul_f32 v[82:83], v[84:85], v[94:95]
	s_nop 0
	v_cndmask_b32_e64 v83, v83, -v83, s[38:39]
	v_cndmask_b32_e64 v82, v82, -v82, s[38:39]
	v_pk_fma_f32 v[68:69], v[68:69], v[96:97], v[82:83]
	ds_bpermute_b32 v82, v102, v70
	ds_bpermute_b32 v83, v102, v71
	v_mov_b32_e32 v85, v80
	v_mov_b32_e32 v80, v79
	v_mov_b32_e32 v84, v78
	s_waitcnt lgkmcnt(0)
	v_pk_mul_f32 v[78:79], v[80:81], v[82:83]
	s_nop 0
	v_cndmask_b32_e64 v79, v79, -v79, s[38:39]
	v_cndmask_b32_e64 v78, v78, -v78, s[38:39]
	v_pk_fma_f32 v[70:71], v[70:71], v[84:85], v[78:79]
	ds_bpermute_b32 v78, v102, v72
	ds_bpermute_b32 v79, v102, v73
	v_mov_b32_e32 v81, v76
	v_mov_b32_e32 v76, v75
	v_mov_b32_e32 v80, v74
	s_waitcnt lgkmcnt(0)
	v_pk_mul_f32 v[74:75], v[76:77], v[78:79]
	s_nop 0
	v_cndmask_b32_e64 v75, v75, -v75, s[38:39]
	v_cndmask_b32_e64 v74, v74, -v74, s[38:39]
	v_pk_fma_f32 v[72:73], v[72:73], v[80:81], v[74:75]
.LBB0_865:
	s_andn2_b64 vcc, exec, s[0:1]
	s_cbranch_vccnz .LBB0_868
	s_lshl_b32 s6, s91, 3
	v_readlane_b32 s7, v241, 60
	s_or_b32 s6, s6, s7
	s_mul_hi_i32 s7, s6, 0x55555556
	s_lshr_b32 vcc_lo, s7, 31
	s_add_i32 s7, s7, vcc_lo
	s_mul_i32 s7, s7, 3
	s_sub_i32 s6, s6, s7
	s_cmp_lg_u32 s6, 2
	s_cbranch_scc1 .LBB0_868
	v_xor_b32_e32 v74, 16, v197
	v_cmp_lt_i32_e32 vcc, v74, v200
	v_lshlrev_b32_e32 v93, 2, v92
	s_nop 0
	v_cndmask_b32_e32 v74, v197, v74, vcc
	v_lshlrev_b32_e32 v102, 2, v74
	v_add_u32_e32 v93, s99, v93
	ds_read_b128 v[74:77], v93 offset:48
	ds_read_b128 v[78:81], v93 offset:32
	ds_read_b128 v[82:85], v93 offset:16
	ds_read_b128 v[94:97], v93
	v_subrev_u32_e32 v93, s99, v93
	ds_bpermute_b32 v98, v102, v66
	ds_bpermute_b32 v99, v102, v67
	s_waitcnt lgkmcnt(0)
	v_mov_b32_e32 v101, v96
	v_mov_b32_e32 v96, v95
	v_mov_b32_e32 v100, v94
	s_waitcnt lgkmcnt(0)
	v_pk_mul_f32 v[94:95], v[96:97], v[98:99]
	v_mov_b32_e32 v97, v84
	v_cndmask_b32_e64 v95, v95, -v95, s[36:37]
	v_cndmask_b32_e64 v94, v94, -v94, s[36:37]
	v_pk_fma_f32 v[66:67], v[66:67], v[100:101], v[94:95]
	ds_bpermute_b32 v94, v102, v68
	ds_bpermute_b32 v95, v102, v69
	v_mov_b32_e32 v84, v83
	v_mov_b32_e32 v96, v82
	s_waitcnt lgkmcnt(0)
	v_pk_mul_f32 v[82:83], v[84:85], v[94:95]
	s_nop 0
	v_cndmask_b32_e64 v83, v83, -v83, s[36:37]
	v_cndmask_b32_e64 v82, v82, -v82, s[36:37]
	v_pk_fma_f32 v[68:69], v[68:69], v[96:97], v[82:83]
	ds_bpermute_b32 v82, v102, v70
	ds_bpermute_b32 v83, v102, v71
	v_mov_b32_e32 v85, v80
	v_mov_b32_e32 v80, v79
	v_mov_b32_e32 v84, v78
	s_waitcnt lgkmcnt(0)
	v_pk_mul_f32 v[78:79], v[80:81], v[82:83]
	s_nop 0
	v_cndmask_b32_e64 v79, v79, -v79, s[36:37]
	v_cndmask_b32_e64 v78, v78, -v78, s[36:37]
	v_pk_fma_f32 v[70:71], v[70:71], v[84:85], v[78:79]
	ds_bpermute_b32 v78, v102, v72
	ds_bpermute_b32 v79, v102, v73
	v_mov_b32_e32 v81, v76
	v_mov_b32_e32 v76, v75
	v_mov_b32_e32 v80, v74
	s_waitcnt lgkmcnt(0)
	v_pk_mul_f32 v[74:75], v[76:77], v[78:79]
	s_nop 0
	v_cndmask_b32_e64 v75, v75, -v75, s[36:37]
	v_cndmask_b32_e64 v74, v74, -v74, s[36:37]
	v_pk_fma_f32 v[72:73], v[72:73], v[80:81], v[74:75]

.LBB0_876:
	v_mov_b64_e32 v[72:73], v[64:65]
	s_and_b64 vcc, exec, s[40:41]
	v_mov_b64_e32 v[70:71], v[62:63]
	v_mov_b64_e32 v[68:69], v[60:61]
	v_mov_b64_e32 v[66:67], v[58:59]
	s_cbranch_vccnz .LBB0_878
	v_and_b32_e32 v66, 32, v167
	v_cmp_eq_u32_e32 vcc, 0, v66
	v_lshlrev_b32_e32 v67, 2, v0
	s_nop 0
	v_cndmask_b32_e32 v66, v88, v89, vcc
	v_cmp_lt_i32_e32 vcc, v198, v200
	v_lshl_or_b32 v66, v66, 7, v67
	s_nop 0
	v_cndmask_b32_e32 v67, v197, v198, vcc
	v_lshlrev_b32_e32 v75, 2, v67
	v_add_u32_e32 v66, s98, v66
	ds_read_b128 v[76:79], v66 offset:48
	ds_read_b128 v[70:73], v66 offset:32
	ds_read_b128 v[80:83], v66 offset:16
	s_nop 0
	ds_read_b128 v[66:69], v66
	ds_bpermute_b32 v84, v75, v58
	ds_bpermute_b32 v85, v75, v59
	s_waitcnt lgkmcnt(0)
	v_mov_b32_e32 v95, v68
	v_mov_b32_e32 v68, v67
	v_mov_b32_e32 v94, v66
	s_waitcnt lgkmcnt(0)
	v_pk_mul_f32 v[66:67], v[68:69], v[84:85]
	ds_bpermute_b32 v68, v75, v60
	ds_bpermute_b32 v69, v75, v61
	v_mov_b32_e32 v84, v80
	v_mov_b32_e32 v85, v82
	v_mov_b32_e32 v82, v81
	ds_bpermute_b32 v80, v75, v62
	ds_bpermute_b32 v81, v75, v63
	s_waitcnt lgkmcnt(2)
	v_pk_mul_f32 v[68:69], v[82:83], v[68:69]
	v_mov_b32_e32 v83, v72
	v_mov_b32_e32 v72, v71
	v_mov_b32_e32 v82, v70
	s_waitcnt lgkmcnt(0)
	v_pk_mul_f32 v[70:71], v[72:73], v[80:81]
	ds_bpermute_b32 v72, v75, v64
	ds_bpermute_b32 v73, v75, v65
	v_mov_b32_e32 v81, v78
	v_mov_b32_e32 v78, v77
	v_cndmask_b32_e64 v67, v67, -v67, s[38:39]
	v_cndmask_b32_e64 v66, v66, -v66, s[38:39]
	s_waitcnt lgkmcnt(0)
	v_pk_mul_f32 v[72:73], v[78:79], v[72:73]
	v_cndmask_b32_e64 v69, v69, -v69, s[38:39]
	v_cndmask_b32_e64 v68, v68, -v68, s[38:39]
	v_cndmask_b32_e64 v71, v71, -v71, s[38:39]
	v_cndmask_b32_e64 v70, v70, -v70, s[38:39]
	v_mov_b32_e32 v80, v76
	v_cndmask_b32_e64 v73, v73, -v73, s[38:39]
	v_cndmask_b32_e64 v72, v72, -v72, s[38:39]
	v_pk_fma_f32 v[66:67], v[58:59], v[94:95], v[66:67]
	v_pk_fma_f32 v[68:69], v[60:61], v[84:85], v[68:69]
	v_pk_fma_f32 v[70:71], v[62:63], v[82:83], v[70:71]
	v_pk_fma_f32 v[72:73], v[64:65], v[80:81], v[72:73]

.LBB0_879:
	s_mov_b64 s[10:11], 0
	s_cbranch_execz .LBB0_888
	s_and_b64 vcc, exec, s[40:41]
	s_cbranch_vccnz .LBB0_882
	v_and_b32_e32 v66, 32, v167
	v_cmp_eq_u32_e32 vcc, 0, v66
	v_lshlrev_b32_e32 v67, 2, v0
	s_nop 0
	v_cndmask_b32_e32 v66, v88, v89, vcc
	v_cmp_lt_i32_e32 vcc, v198, v200
	v_lshl_or_b32 v78, v66, 7, v67
	s_nop 0
	v_cndmask_b32_e32 v66, v197, v198, vcc
	v_lshlrev_b32_e32 v88, 2, v66
	v_add_u32_e32 v78, s98, v78
	ds_read_b128 v[66:69], v78 offset:48
	ds_read_b128 v[70:73], v78 offset:32
	ds_read_b128 v[74:77], v78 offset:16
	s_nop 0
	ds_read_b128 v[78:81], v78
	ds_bpermute_b32 v82, v88, v58
	ds_bpermute_b32 v83, v88, v59
	s_waitcnt lgkmcnt(0)
	v_mov_b32_e32 v85, v80
	v_mov_b32_e32 v80, v79
	v_mov_b32_e32 v84, v78
	s_waitcnt lgkmcnt(0)
	v_pk_mul_f32 v[78:79], v[80:81], v[82:83]
	v_mov_b32_e32 v81, v76
	v_cndmask_b32_e64 v79, v79, -v79, s[38:39]
	v_cndmask_b32_e64 v78, v78, -v78, s[38:39]
	v_pk_fma_f32 v[58:59], v[58:59], v[84:85], v[78:79]
	ds_bpermute_b32 v78, v88, v60
	ds_bpermute_b32 v79, v88, v61
	v_mov_b32_e32 v76, v75
	v_mov_b32_e32 v80, v74
	s_waitcnt lgkmcnt(0)
	v_pk_mul_f32 v[74:75], v[76:77], v[78:79]
	s_nop 0
	v_cndmask_b32_e64 v75, v75, -v75, s[38:39]
	v_cndmask_b32_e64 v74, v74, -v74, s[38:39]
	v_pk_fma_f32 v[60:61], v[60:61], v[80:81], v[74:75]
	ds_bpermute_b32 v74, v88, v62
	ds_bpermute_b32 v75, v88, v63
	v_mov_b32_e32 v77, v72
	v_mov_b32_e32 v72, v71
	v_mov_b32_e32 v76, v70
	s_waitcnt lgkmcnt(0)
	v_pk_mul_f32 v[70:71], v[72:73], v[74:75]
	s_nop 0
	v_cndmask_b32_e64 v71, v71, -v71, s[38:39]
	v_cndmask_b32_e64 v70, v70, -v70, s[38:39]
	v_pk_fma_f32 v[62:63], v[62:63], v[76:77], v[70:71]
	ds_bpermute_b32 v70, v88, v64
	ds_bpermute_b32 v71, v88, v65
	v_mov_b32_e32 v73, v68
	v_mov_b32_e32 v68, v67
	v_mov_b32_e32 v72, v66
	s_waitcnt lgkmcnt(0)
	v_pk_mul_f32 v[66:67], v[68:69], v[70:71]
	s_nop 0
	v_cndmask_b32_e64 v67, v67, -v67, s[38:39]
	v_cndmask_b32_e64 v66, v66, -v66, s[38:39]
	v_pk_fma_f32 v[64:65], v[64:65], v[72:73], v[66:67]
.LBB0_882:
	s_andn2_b64 vcc, exec, s[0:1]
	s_cbranch_vccnz .LBB0_885
	s_lshl_b32 s6, s91, 3
	v_readlane_b32 s7, v241, 61
	s_or_b32 s6, s6, s7
	s_mul_hi_i32 s7, s6, 0x55555556
	s_lshr_b32 vcc_lo, s7, 31
	s_add_i32 s7, s7, vcc_lo
	s_mul_i32 s7, s7, 3
	s_sub_i32 s6, s6, s7
	s_cmp_lg_u32 s6, 2
	s_cbranch_scc1 .LBB0_885
	v_xor_b32_e32 v66, 16, v197
	v_cmp_lt_i32_e32 vcc, v66, v200
	v_lshlrev_b32_e32 v78, 2, v92
	s_nop 0
	v_cndmask_b32_e32 v66, v197, v66, vcc
	v_lshlrev_b32_e32 v88, 2, v66
	v_add_u32_e32 v78, s99, v78
	ds_read_b128 v[66:69], v78 offset:48
	ds_read_b128 v[70:73], v78 offset:32
	ds_read_b128 v[74:77], v78 offset:16
	s_nop 0
	ds_read_b128 v[78:81], v78
	ds_bpermute_b32 v82, v88, v58
	ds_bpermute_b32 v83, v88, v59
	s_waitcnt lgkmcnt(0)
	v_mov_b32_e32 v85, v80
	v_mov_b32_e32 v80, v79
	v_mov_b32_e32 v84, v78
	s_waitcnt lgkmcnt(0)
	v_pk_mul_f32 v[78:79], v[80:81], v[82:83]
	v_mov_b32_e32 v81, v76
	v_cndmask_b32_e64 v79, v79, -v79, s[36:37]
	v_cndmask_b32_e64 v78, v78, -v78, s[36:37]
	v_pk_fma_f32 v[58:59], v[58:59], v[84:85], v[78:79]
	ds_bpermute_b32 v78, v88, v60
	ds_bpermute_b32 v79, v88, v61
	v_mov_b32_e32 v76, v75
	v_mov_b32_e32 v80, v74
	s_waitcnt lgkmcnt(0)
	v_pk_mul_f32 v[74:75], v[76:77], v[78:79]
	s_nop 0
	v_cndmask_b32_e64 v75, v75, -v75, s[36:37]
	v_cndmask_b32_e64 v74, v74, -v74, s[36:37]
	v_pk_fma_f32 v[60:61], v[60:61], v[80:81], v[74:75]
	ds_bpermute_b32 v74, v88, v62
	ds_bpermute_b32 v75, v88, v63
	v_mov_b32_e32 v77, v72
	v_mov_b32_e32 v72, v71
	v_mov_b32_e32 v76, v70
	s_waitcnt lgkmcnt(0)
	v_pk_mul_f32 v[70:71], v[72:73], v[74:75]
	s_nop 0
	v_cndmask_b32_e64 v71, v71, -v71, s[36:37]
	v_cndmask_b32_e64 v70, v70, -v70, s[36:37]
	v_pk_fma_f32 v[62:63], v[62:63], v[76:77], v[70:71]
	ds_bpermute_b32 v70, v88, v64
	ds_bpermute_b32 v71, v88, v65
	v_mov_b32_e32 v73, v68
	v_mov_b32_e32 v68, v67
	v_mov_b32_e32 v72, v66
	s_waitcnt lgkmcnt(0)
	v_pk_mul_f32 v[66:67], v[68:69], v[70:71]
	s_nop 0
	v_cndmask_b32_e64 v67, v67, -v67, s[36:37]
	v_cndmask_b32_e64 v66, v66, -v66, s[36:37]
	v_pk_fma_f32 v[64:65], v[64:65], v[72:73], v[66:67]

.LBB0_895:
	v_mov_b64_e32 v[64:65], v[56:57]
	s_and_b64 vcc, exec, s[40:41]
	v_mov_b64_e32 v[62:63], v[54:55]
	v_mov_b64_e32 v[60:61], v[52:53]
	v_mov_b64_e32 v[58:59], v[50:51]
	s_cbranch_vccnz .LBB0_897
	v_and_b32_e32 v58, 32, v167
	v_cmp_eq_u32_e32 vcc, 0, v58
	v_lshlrev_b32_e32 v59, 2, v0
	s_nop 0
	v_cndmask_b32_e32 v58, v72, v73, vcc
	v_cmp_lt_i32_e32 vcc, v198, v200
	v_lshl_or_b32 v58, v58, 7, v59
	s_nop 0
	v_cndmask_b32_e32 v59, v197, v198, vcc
	v_lshlrev_b32_e32 v67, 2, v59
	v_add_u32_e32 v58, s98, v58
	ds_read_b128 v[76:79], v58 offset:48
	ds_read_b128 v[62:65], v58 offset:32
	ds_read_b128 v[80:83], v58 offset:16
	s_nop 0
	ds_read_b128 v[58:61], v58
	ds_bpermute_b32 v68, v67, v50
	ds_bpermute_b32 v69, v67, v51
	s_waitcnt lgkmcnt(0)
	v_mov_b32_e32 v85, v60
	v_mov_b32_e32 v60, v59
	v_mov_b32_e32 v84, v58
	s_waitcnt lgkmcnt(0)
	v_pk_mul_f32 v[58:59], v[60:61], v[68:69]
	ds_bpermute_b32 v60, v67, v52
	ds_bpermute_b32 v61, v67, v53
	v_mov_b32_e32 v69, v82
	v_mov_b32_e32 v82, v81
	v_mov_b32_e32 v68, v80
	v_mov_b32_e32 v81, v64
	s_waitcnt lgkmcnt(0)
	v_pk_mul_f32 v[60:61], v[82:83], v[60:61]
	v_mov_b32_e32 v64, v63
	v_cndmask_b32_e64 v61, v61, -v61, s[38:39]
	v_cndmask_b32_e64 v60, v60, -v60, s[38:39]
	v_pk_fma_f32 v[60:61], v[52:53], v[68:69], v[60:61]
	ds_bpermute_b32 v68, v67, v54
	ds_bpermute_b32 v69, v67, v55
	v_mov_b32_e32 v80, v62
	v_cndmask_b32_e64 v59, v59, -v59, s[38:39]
	v_cndmask_b32_e64 v58, v58, -v58, s[38:39]
	v_pk_fma_f32 v[58:59], v[50:51], v[84:85], v[58:59]
	s_waitcnt lgkmcnt(0)
	v_pk_mul_f32 v[62:63], v[64:65], v[68:69]
	ds_bpermute_b32 v64, v67, v56
	ds_bpermute_b32 v65, v67, v57
	v_mov_b32_e32 v69, v78
	v_mov_b32_e32 v78, v77
	v_cndmask_b32_e64 v63, v63, -v63, s[38:39]
	v_cndmask_b32_e64 v62, v62, -v62, s[38:39]
	s_waitcnt lgkmcnt(0)
	v_pk_mul_f32 v[64:65], v[78:79], v[64:65]
	v_mov_b32_e32 v68, v76
	v_cndmask_b32_e64 v65, v65, -v65, s[38:39]
	v_cndmask_b32_e64 v64, v64, -v64, s[38:39]
	v_pk_fma_f32 v[62:63], v[54:55], v[80:81], v[62:63]
	v_pk_fma_f32 v[64:65], v[56:57], v[68:69], v[64:65]

.LBB0_898:
	s_mov_b64 s[10:11], 0
	v_cndmask_b32_e64 v67, v72, v73, s[38:39]
	v_lshlrev_b32_e32 v76, 4, v67
	s_cbranch_execz .LBB0_907
	s_and_b64 vcc, exec, s[40:41]
	s_cbranch_vccnz .LBB0_901
	v_and_b32_e32 v58, 32, v167
	v_cmp_eq_u32_e32 vcc, 0, v58
	v_lshlrev_b32_e32 v59, 2, v0
	s_nop 0
	v_cndmask_b32_e32 v58, v72, v73, vcc
	v_cmp_lt_i32_e32 vcc, v198, v200
	v_lshl_or_b32 v77, v58, 7, v59
	s_nop 0
	v_cndmask_b32_e32 v58, v197, v198, vcc
	v_lshlrev_b32_e32 v86, 2, v58
	v_add_u32_e32 v77, s98, v77
	ds_read_b128 v[58:61], v77 offset:48
	ds_read_b128 v[62:65], v77 offset:32
	ds_read_b128 v[66:69], v77 offset:16
	ds_read_b128 v[78:81], v77
	v_subrev_u32_e32 v77, s98, v77
	ds_bpermute_b32 v82, v86, v50
	ds_bpermute_b32 v83, v86, v51
	s_waitcnt lgkmcnt(0)
	v_mov_b32_e32 v85, v80
	v_mov_b32_e32 v80, v79
	v_mov_b32_e32 v84, v78
	s_waitcnt lgkmcnt(0)
	v_pk_mul_f32 v[78:79], v[80:81], v[82:83]
	v_mov_b32_e32 v81, v68
	v_cndmask_b32_e64 v79, v79, -v79, s[38:39]
	v_cndmask_b32_e64 v78, v78, -v78, s[38:39]
	v_pk_fma_f32 v[50:51], v[50:51], v[84:85], v[78:79]
	ds_bpermute_b32 v78, v86, v52
	ds_bpermute_b32 v79, v86, v53
	v_mov_b32_e32 v68, v67
	v_mov_b32_e32 v80, v66
	s_waitcnt lgkmcnt(0)
	v_pk_mul_f32 v[66:67], v[68:69], v[78:79]
	s_nop 0
	v_cndmask_b32_e64 v67, v67, -v67, s[38:39]
	v_cndmask_b32_e64 v66, v66, -v66, s[38:39]
	v_pk_fma_f32 v[52:53], v[52:53], v[80:81], v[66:67]
	ds_bpermute_b32 v66, v86, v54
	ds_bpermute_b32 v67, v86, v55
	v_mov_b32_e32 v69, v64
	v_mov_b32_e32 v64, v63
	v_mov_b32_e32 v68, v62
	s_waitcnt lgkmcnt(0)
	v_pk_mul_f32 v[62:63], v[64:65], v[66:67]
	s_nop 0
	v_cndmask_b32_e64 v63, v63, -v63, s[38:39]
	v_cndmask_b32_e64 v62, v62, -v62, s[38:39]
	v_pk_fma_f32 v[54:55], v[54:55], v[68:69], v[62:63]
	ds_bpermute_b32 v62, v86, v56
	ds_bpermute_b32 v63, v86, v57
	v_mov_b32_e32 v65, v60
	v_mov_b32_e32 v60, v59
	v_mov_b32_e32 v64, v58
	s_waitcnt lgkmcnt(0)
	v_pk_mul_f32 v[58:59], v[60:61], v[62:63]
	s_nop 0
	v_cndmask_b32_e64 v59, v59, -v59, s[38:39]
	v_cndmask_b32_e64 v58, v58, -v58, s[38:39]
	v_pk_fma_f32 v[56:57], v[56:57], v[64:65], v[58:59]
.LBB0_901:
	s_andn2_b64 vcc, exec, s[0:1]
	s_cbranch_vccnz .LBB0_904
	s_lshl_b32 s6, s91, 3
	v_readlane_b32 s7, v241, 60
	s_or_b32 s6, s6, s7
	s_mul_hi_i32 s7, s6, 0x55555556
	s_lshr_b32 vcc_lo, s7, 31
	s_add_i32 s7, s7, vcc_lo
	s_mul_i32 s7, s7, 3
	s_sub_i32 s6, s6, s7
	s_cmp_lg_u32 s6, 2
	s_cbranch_scc1 .LBB0_904
	v_xor_b32_e32 v58, 16, v197
	v_cmp_lt_i32_e32 vcc, v58, v200
	v_lshlrev_b32_e32 v77, 2, v76
	s_nop 0
	v_cndmask_b32_e32 v58, v197, v58, vcc
	v_lshlrev_b32_e32 v86, 2, v58
	v_add_u32_e32 v77, s99, v77
	ds_read_b128 v[58:61], v77 offset:48
	ds_read_b128 v[62:65], v77 offset:32
	ds_read_b128 v[66:69], v77 offset:16
	ds_read_b128 v[78:81], v77
	v_subrev_u32_e32 v77, s99, v77
	ds_bpermute_b32 v82, v86, v50
	ds_bpermute_b32 v83, v86, v51
	s_waitcnt lgkmcnt(0)
	v_mov_b32_e32 v85, v80
	v_mov_b32_e32 v80, v79
	v_mov_b32_e32 v84, v78
	s_waitcnt lgkmcnt(0)
	v_pk_mul_f32 v[78:79], v[80:81], v[82:83]
	v_mov_b32_e32 v81, v68
	v_cndmask_b32_e64 v79, v79, -v79, s[36:37]
	v_cndmask_b32_e64 v78, v78, -v78, s[36:37]
	v_pk_fma_f32 v[50:51], v[50:51], v[84:85], v[78:79]
	ds_bpermute_b32 v78, v86, v52
	ds_bpermute_b32 v79, v86, v53
	v_mov_b32_e32 v68, v67
	v_mov_b32_e32 v80, v66
	s_waitcnt lgkmcnt(0)
	v_pk_mul_f32 v[66:67], v[68:69], v[78:79]
	s_nop 0
	v_cndmask_b32_e64 v67, v67, -v67, s[36:37]
	v_cndmask_b32_e64 v66, v66, -v66, s[36:37]
	v_pk_fma_f32 v[52:53], v[52:53], v[80:81], v[66:67]
	ds_bpermute_b32 v66, v86, v54
	ds_bpermute_b32 v67, v86, v55
	v_mov_b32_e32 v69, v64
	v_mov_b32_e32 v64, v63
	v_mov_b32_e32 v68, v62
	s_waitcnt lgkmcnt(0)
	v_pk_mul_f32 v[62:63], v[64:65], v[66:67]
	s_nop 0
	v_cndmask_b32_e64 v63, v63, -v63, s[36:37]
	v_cndmask_b32_e64 v62, v62, -v62, s[36:37]
	v_pk_fma_f32 v[54:55], v[54:55], v[68:69], v[62:63]
	ds_bpermute_b32 v62, v86, v56
	ds_bpermute_b32 v63, v86, v57
	v_mov_b32_e32 v65, v60
	v_mov_b32_e32 v60, v59
	v_mov_b32_e32 v64, v58
	s_waitcnt lgkmcnt(0)
	v_pk_mul_f32 v[58:59], v[60:61], v[62:63]
	s_nop 0
	v_cndmask_b32_e64 v59, v59, -v59, s[36:37]
	v_cndmask_b32_e64 v58, v58, -v58, s[36:37]
	v_pk_fma_f32 v[56:57], v[56:57], v[64:65], v[58:59]

.LBB0_912:
	v_mov_b64_e32 v[56:57], v[48:49]
	s_and_b64 vcc, exec, s[40:41]
	v_mov_b64_e32 v[54:55], v[46:47]
	v_mov_b64_e32 v[52:53], v[44:45]
	v_mov_b64_e32 v[50:51], v[42:43]
	s_cbranch_vccnz .LBB0_914
	v_and_b32_e32 v50, 32, v167
	v_cmp_eq_u32_e32 vcc, 0, v50
	v_lshlrev_b32_e32 v51, 2, v0
	s_nop 0
	v_cndmask_b32_e32 v50, v72, v73, vcc
	v_cmp_lt_i32_e32 vcc, v198, v200
	v_lshl_or_b32 v50, v50, 7, v51
	s_nop 0
	v_cndmask_b32_e32 v51, v197, v198, vcc
	v_lshlrev_b32_e32 v59, 2, v51
	v_add_u32_e32 v50, s98, v50
	ds_read_b128 v[60:63], v50 offset:48
	ds_read_b128 v[54:57], v50 offset:32
	ds_read_b128 v[64:67], v50 offset:16
	s_nop 0
	ds_read_b128 v[50:53], v50
	ds_bpermute_b32 v68, v59, v42
	ds_bpermute_b32 v69, v59, v43
	s_waitcnt lgkmcnt(0)
	v_mov_b32_e32 v79, v52
	v_mov_b32_e32 v52, v51
	v_mov_b32_e32 v78, v50
	s_waitcnt lgkmcnt(0)
	v_pk_mul_f32 v[50:51], v[52:53], v[68:69]
	ds_bpermute_b32 v52, v59, v44
	ds_bpermute_b32 v53, v59, v45
	v_mov_b32_e32 v68, v64
	v_mov_b32_e32 v69, v66
	v_mov_b32_e32 v66, v65
	ds_bpermute_b32 v64, v59, v46
	ds_bpermute_b32 v65, v59, v47
	s_waitcnt lgkmcnt(2)
	v_pk_mul_f32 v[52:53], v[66:67], v[52:53]
	v_mov_b32_e32 v67, v56
	v_mov_b32_e32 v56, v55
	v_mov_b32_e32 v66, v54
	s_waitcnt lgkmcnt(0)
	v_pk_mul_f32 v[54:55], v[56:57], v[64:65]
	ds_bpermute_b32 v56, v59, v48
	ds_bpermute_b32 v57, v59, v49
	v_mov_b32_e32 v65, v62
	v_mov_b32_e32 v62, v61
	v_cndmask_b32_e64 v51, v51, -v51, s[38:39]
	v_cndmask_b32_e64 v50, v50, -v50, s[38:39]
	s_waitcnt lgkmcnt(0)
	v_pk_mul_f32 v[56:57], v[62:63], v[56:57]
	v_cndmask_b32_e64 v53, v53, -v53, s[38:39]
	v_cndmask_b32_e64 v52, v52, -v52, s[38:39]
	v_cndmask_b32_e64 v55, v55, -v55, s[38:39]
	v_cndmask_b32_e64 v54, v54, -v54, s[38:39]
	v_mov_b32_e32 v64, v60
	v_cndmask_b32_e64 v57, v57, -v57, s[38:39]
	v_cndmask_b32_e64 v56, v56, -v56, s[38:39]
	v_pk_fma_f32 v[50:51], v[42:43], v[78:79], v[50:51]
	v_pk_fma_f32 v[52:53], v[44:45], v[68:69], v[52:53]
	v_pk_fma_f32 v[54:55], v[46:47], v[66:67], v[54:55]
	v_pk_fma_f32 v[56:57], v[48:49], v[64:65], v[56:57]

.LBB0_915:
	s_mov_b64 s[10:11], 0
	s_cbranch_execz .LBB0_924
	s_and_b64 vcc, exec, s[40:41]
	s_cbranch_vccnz .LBB0_918
	v_and_b32_e32 v50, 32, v167
	v_cmp_eq_u32_e32 vcc, 0, v50
	v_lshlrev_b32_e32 v51, 2, v0
	s_nop 0
	v_cndmask_b32_e32 v50, v72, v73, vcc
	v_cmp_lt_i32_e32 vcc, v198, v200
	v_lshl_or_b32 v62, v50, 7, v51
	s_nop 0
	v_cndmask_b32_e32 v50, v197, v198, vcc
	v_lshlrev_b32_e32 v72, 2, v50
	v_add_u32_e32 v62, s98, v62
	ds_read_b128 v[50:53], v62 offset:48
	ds_read_b128 v[54:57], v62 offset:32
	ds_read_b128 v[58:61], v62 offset:16
	s_nop 0
	ds_read_b128 v[62:65], v62
	ds_bpermute_b32 v66, v72, v42
	ds_bpermute_b32 v67, v72, v43
	s_waitcnt lgkmcnt(0)
	v_mov_b32_e32 v69, v64
	v_mov_b32_e32 v64, v63
	v_mov_b32_e32 v68, v62
	s_waitcnt lgkmcnt(0)
	v_pk_mul_f32 v[62:63], v[64:65], v[66:67]
	v_mov_b32_e32 v65, v60
	v_cndmask_b32_e64 v63, v63, -v63, s[38:39]
	v_cndmask_b32_e64 v62, v62, -v62, s[38:39]
	v_pk_fma_f32 v[42:43], v[42:43], v[68:69], v[62:63]
	ds_bpermute_b32 v62, v72, v44
	ds_bpermute_b32 v63, v72, v45
	v_mov_b32_e32 v60, v59
	v_mov_b32_e32 v64, v58
	s_waitcnt lgkmcnt(0)
	v_pk_mul_f32 v[58:59], v[60:61], v[62:63]
	s_nop 0
	v_cndmask_b32_e64 v59, v59, -v59, s[38:39]
	v_cndmask_b32_e64 v58, v58, -v58, s[38:39]
	v_pk_fma_f32 v[44:45], v[44:45], v[64:65], v[58:59]
	ds_bpermute_b32 v58, v72, v46
	ds_bpermute_b32 v59, v72, v47
	v_mov_b32_e32 v61, v56
	v_mov_b32_e32 v56, v55
	v_mov_b32_e32 v60, v54
	s_waitcnt lgkmcnt(0)
	v_pk_mul_f32 v[54:55], v[56:57], v[58:59]
	s_nop 0
	v_cndmask_b32_e64 v55, v55, -v55, s[38:39]
	v_cndmask_b32_e64 v54, v54, -v54, s[38:39]
	v_pk_fma_f32 v[46:47], v[46:47], v[60:61], v[54:55]
	ds_bpermute_b32 v54, v72, v48
	ds_bpermute_b32 v55, v72, v49
	v_mov_b32_e32 v57, v52
	v_mov_b32_e32 v52, v51
	v_mov_b32_e32 v56, v50
	s_waitcnt lgkmcnt(0)
	v_pk_mul_f32 v[50:51], v[52:53], v[54:55]
	s_nop 0
	v_cndmask_b32_e64 v51, v51, -v51, s[38:39]
	v_cndmask_b32_e64 v50, v50, -v50, s[38:39]
	v_pk_fma_f32 v[48:49], v[48:49], v[56:57], v[50:51]
.LBB0_918:
	s_andn2_b64 vcc, exec, s[0:1]
	s_cbranch_vccnz .LBB0_921
	s_lshl_b32 s6, s91, 3
	v_readlane_b32 s7, v241, 61
	s_or_b32 s6, s6, s7
	s_mul_hi_i32 s7, s6, 0x55555556
	s_lshr_b32 vcc_lo, s7, 31
	s_add_i32 s7, s7, vcc_lo
	s_mul_i32 s7, s7, 3
	s_sub_i32 s6, s6, s7
	s_cmp_lg_u32 s6, 2
	s_cbranch_scc1 .LBB0_921
	v_xor_b32_e32 v50, 16, v197
	v_cmp_lt_i32_e32 vcc, v50, v200
	v_lshlrev_b32_e32 v62, 2, v76
	s_nop 0
	v_cndmask_b32_e32 v50, v197, v50, vcc
	v_lshlrev_b32_e32 v72, 2, v50
	v_add_u32_e32 v62, s99, v62
	ds_read_b128 v[50:53], v62 offset:48
	ds_read_b128 v[54:57], v62 offset:32
	ds_read_b128 v[58:61], v62 offset:16
	s_nop 0
	ds_read_b128 v[62:65], v62
	ds_bpermute_b32 v66, v72, v42
	ds_bpermute_b32 v67, v72, v43
	s_waitcnt lgkmcnt(0)
	v_mov_b32_e32 v69, v64
	v_mov_b32_e32 v64, v63
	v_mov_b32_e32 v68, v62
	s_waitcnt lgkmcnt(0)
	v_pk_mul_f32 v[62:63], v[64:65], v[66:67]
	v_mov_b32_e32 v65, v60
	v_cndmask_b32_e64 v63, v63, -v63, s[36:37]
	v_cndmask_b32_e64 v62, v62, -v62, s[36:37]
	v_pk_fma_f32 v[42:43], v[42:43], v[68:69], v[62:63]
	ds_bpermute_b32 v62, v72, v44
	ds_bpermute_b32 v63, v72, v45
	v_mov_b32_e32 v60, v59
	v_mov_b32_e32 v64, v58
	s_waitcnt lgkmcnt(0)
	v_pk_mul_f32 v[58:59], v[60:61], v[62:63]
	s_nop 0
	v_cndmask_b32_e64 v59, v59, -v59, s[36:37]
	v_cndmask_b32_e64 v58, v58, -v58, s[36:37]
	v_pk_fma_f32 v[44:45], v[44:45], v[64:65], v[58:59]
	ds_bpermute_b32 v58, v72, v46
	ds_bpermute_b32 v59, v72, v47
	v_mov_b32_e32 v61, v56
	v_mov_b32_e32 v56, v55
	v_mov_b32_e32 v60, v54
	s_waitcnt lgkmcnt(0)
	v_pk_mul_f32 v[54:55], v[56:57], v[58:59]
	s_nop 0
	v_cndmask_b32_e64 v55, v55, -v55, s[36:37]
	v_cndmask_b32_e64 v54, v54, -v54, s[36:37]
	v_pk_fma_f32 v[46:47], v[46:47], v[60:61], v[54:55]
	ds_bpermute_b32 v54, v72, v48
	ds_bpermute_b32 v55, v72, v49
	v_mov_b32_e32 v57, v52
	v_mov_b32_e32 v52, v51
	v_mov_b32_e32 v56, v50
	s_waitcnt lgkmcnt(0)
	v_pk_mul_f32 v[50:51], v[52:53], v[54:55]
	s_nop 0
	v_cndmask_b32_e64 v51, v51, -v51, s[36:37]
	v_cndmask_b32_e64 v50, v50, -v50, s[36:37]
	v_pk_fma_f32 v[48:49], v[48:49], v[56:57], v[50:51]

.LBB0_931:
	v_mov_b64_e32 v[48:49], v[40:41]
	s_and_b64 vcc, exec, s[40:41]
	v_mov_b64_e32 v[46:47], v[38:39]
	v_mov_b64_e32 v[44:45], v[36:37]
	v_mov_b64_e32 v[42:43], v[34:35]
	s_cbranch_vccnz .LBB0_933
	v_and_b32_e32 v42, 32, v167
	v_cmp_eq_u32_e32 vcc, 0, v42
	v_lshlrev_b32_e32 v43, 2, v0
	s_nop 0
	v_cndmask_b32_e32 v42, v56, v57, vcc
	v_cmp_lt_i32_e32 vcc, v198, v200
	v_lshl_or_b32 v42, v42, 7, v43
	s_nop 0
	v_cndmask_b32_e32 v43, v197, v198, vcc
	v_lshlrev_b32_e32 v51, 2, v43
	v_add_u32_e32 v42, s98, v42
	ds_read_b128 v[60:63], v42 offset:48
	ds_read_b128 v[46:49], v42 offset:32
	ds_read_b128 v[64:67], v42 offset:16
	s_nop 0
	ds_read_b128 v[42:45], v42
	ds_bpermute_b32 v52, v51, v34
	ds_bpermute_b32 v53, v51, v35
	s_waitcnt lgkmcnt(0)
	v_mov_b32_e32 v69, v44
	v_mov_b32_e32 v44, v43
	v_mov_b32_e32 v68, v42
	s_waitcnt lgkmcnt(0)
	v_pk_mul_f32 v[42:43], v[44:45], v[52:53]
	ds_bpermute_b32 v44, v51, v36
	ds_bpermute_b32 v45, v51, v37
	v_mov_b32_e32 v53, v66
	v_mov_b32_e32 v66, v65
	v_mov_b32_e32 v52, v64
	v_mov_b32_e32 v65, v48
	s_waitcnt lgkmcnt(0)
	v_pk_mul_f32 v[44:45], v[66:67], v[44:45]
	v_mov_b32_e32 v48, v47
	v_cndmask_b32_e64 v45, v45, -v45, s[38:39]
	v_cndmask_b32_e64 v44, v44, -v44, s[38:39]
	v_pk_fma_f32 v[44:45], v[36:37], v[52:53], v[44:45]
	ds_bpermute_b32 v52, v51, v38
	ds_bpermute_b32 v53, v51, v39
	v_mov_b32_e32 v64, v46
	v_cndmask_b32_e64 v43, v43, -v43, s[38:39]
	v_cndmask_b32_e64 v42, v42, -v42, s[38:39]
	v_pk_fma_f32 v[42:43], v[34:35], v[68:69], v[42:43]
	s_waitcnt lgkmcnt(0)
	v_pk_mul_f32 v[46:47], v[48:49], v[52:53]
	ds_bpermute_b32 v48, v51, v40
	ds_bpermute_b32 v49, v51, v41
	v_mov_b32_e32 v53, v62
	v_mov_b32_e32 v62, v61
	v_cndmask_b32_e64 v47, v47, -v47, s[38:39]
	v_cndmask_b32_e64 v46, v46, -v46, s[38:39]
	s_waitcnt lgkmcnt(0)
	v_pk_mul_f32 v[48:49], v[62:63], v[48:49]
	v_mov_b32_e32 v52, v60
	v_cndmask_b32_e64 v49, v49, -v49, s[38:39]
	v_cndmask_b32_e64 v48, v48, -v48, s[38:39]
	v_pk_fma_f32 v[46:47], v[38:39], v[64:65], v[46:47]
	v_pk_fma_f32 v[48:49], v[40:41], v[52:53], v[48:49]

.LBB0_934:
	s_mov_b64 s[10:11], 0
	v_cndmask_b32_e64 v51, v56, v57, s[38:39]
	v_lshlrev_b32_e32 v60, 4, v51
	s_cbranch_execz .LBB0_943
	s_and_b64 vcc, exec, s[40:41]
	s_cbranch_vccnz .LBB0_937
	v_and_b32_e32 v42, 32, v167
	v_cmp_eq_u32_e32 vcc, 0, v42
	v_lshlrev_b32_e32 v43, 2, v0
	s_nop 0
	v_cndmask_b32_e32 v42, v56, v57, vcc
	v_cmp_lt_i32_e32 vcc, v198, v200
	v_lshl_or_b32 v61, v42, 7, v43
	s_nop 0
	v_cndmask_b32_e32 v42, v197, v198, vcc
	v_lshlrev_b32_e32 v71, 2, v42
	v_add_u32_e32 v61, s98, v61
	ds_read_b128 v[42:45], v61 offset:48
	ds_read_b128 v[46:49], v61 offset:32
	ds_read_b128 v[50:53], v61 offset:16
	ds_read_b128 v[62:65], v61
	v_subrev_u32_e32 v61, s98, v61
	ds_bpermute_b32 v66, v71, v34
	ds_bpermute_b32 v67, v71, v35
	s_waitcnt lgkmcnt(0)
	v_mov_b32_e32 v69, v64
	v_mov_b32_e32 v64, v63
	v_mov_b32_e32 v68, v62
	s_waitcnt lgkmcnt(0)
	v_pk_mul_f32 v[62:63], v[64:65], v[66:67]
	v_mov_b32_e32 v65, v52
	v_cndmask_b32_e64 v63, v63, -v63, s[38:39]
	v_cndmask_b32_e64 v62, v62, -v62, s[38:39]
	v_pk_fma_f32 v[34:35], v[34:35], v[68:69], v[62:63]
	ds_bpermute_b32 v62, v71, v36
	ds_bpermute_b32 v63, v71, v37
	v_mov_b32_e32 v52, v51
	v_mov_b32_e32 v64, v50
	s_waitcnt lgkmcnt(0)
	v_pk_mul_f32 v[50:51], v[52:53], v[62:63]
	s_nop 0
	v_cndmask_b32_e64 v51, v51, -v51, s[38:39]
	v_cndmask_b32_e64 v50, v50, -v50, s[38:39]
	v_pk_fma_f32 v[36:37], v[36:37], v[64:65], v[50:51]
	ds_bpermute_b32 v50, v71, v38
	ds_bpermute_b32 v51, v71, v39
	v_mov_b32_e32 v53, v48
	v_mov_b32_e32 v48, v47
	v_mov_b32_e32 v52, v46
	s_waitcnt lgkmcnt(0)
	v_pk_mul_f32 v[46:47], v[48:49], v[50:51]
	s_nop 0
	v_cndmask_b32_e64 v47, v47, -v47, s[38:39]
	v_cndmask_b32_e64 v46, v46, -v46, s[38:39]
	v_pk_fma_f32 v[38:39], v[38:39], v[52:53], v[46:47]
	ds_bpermute_b32 v46, v71, v40
	ds_bpermute_b32 v47, v71, v41
	v_mov_b32_e32 v49, v44
	v_mov_b32_e32 v44, v43
	v_mov_b32_e32 v48, v42
	s_waitcnt lgkmcnt(0)
	v_pk_mul_f32 v[42:43], v[44:45], v[46:47]
	s_nop 0
	v_cndmask_b32_e64 v43, v43, -v43, s[38:39]
	v_cndmask_b32_e64 v42, v42, -v42, s[38:39]
	v_pk_fma_f32 v[40:41], v[40:41], v[48:49], v[42:43]
.LBB0_937:
	s_andn2_b64 vcc, exec, s[0:1]
	s_cbranch_vccnz .LBB0_940
	s_lshl_b32 s6, s91, 3
	v_readlane_b32 s7, v241, 60
	s_or_b32 s6, s6, s7
	s_mul_hi_i32 s7, s6, 0x55555556
	s_lshr_b32 vcc_lo, s7, 31
	s_add_i32 s7, s7, vcc_lo
	s_mul_i32 s7, s7, 3
	s_sub_i32 s6, s6, s7
	s_cmp_lg_u32 s6, 2
	s_cbranch_scc1 .LBB0_940
	v_xor_b32_e32 v42, 16, v197
	v_cmp_lt_i32_e32 vcc, v42, v200
	v_lshlrev_b32_e32 v61, 2, v60
	s_nop 0
	v_cndmask_b32_e32 v42, v197, v42, vcc
	v_lshlrev_b32_e32 v71, 2, v42
	v_add_u32_e32 v61, s99, v61
	ds_read_b128 v[42:45], v61 offset:48
	ds_read_b128 v[46:49], v61 offset:32
	ds_read_b128 v[50:53], v61 offset:16
	ds_read_b128 v[62:65], v61
	v_subrev_u32_e32 v61, s99, v61
	ds_bpermute_b32 v66, v71, v34
	ds_bpermute_b32 v67, v71, v35
	s_waitcnt lgkmcnt(0)
	v_mov_b32_e32 v69, v64
	v_mov_b32_e32 v64, v63
	v_mov_b32_e32 v68, v62
	s_waitcnt lgkmcnt(0)
	v_pk_mul_f32 v[62:63], v[64:65], v[66:67]
	v_mov_b32_e32 v65, v52
	v_cndmask_b32_e64 v63, v63, -v63, s[36:37]
	v_cndmask_b32_e64 v62, v62, -v62, s[36:37]
	v_pk_fma_f32 v[34:35], v[34:35], v[68:69], v[62:63]
	ds_bpermute_b32 v62, v71, v36
	ds_bpermute_b32 v63, v71, v37
	v_mov_b32_e32 v52, v51
	v_mov_b32_e32 v64, v50
	s_waitcnt lgkmcnt(0)
	v_pk_mul_f32 v[50:51], v[52:53], v[62:63]
	s_nop 0
	v_cndmask_b32_e64 v51, v51, -v51, s[36:37]
	v_cndmask_b32_e64 v50, v50, -v50, s[36:37]
	v_pk_fma_f32 v[36:37], v[36:37], v[64:65], v[50:51]
	ds_bpermute_b32 v50, v71, v38
	ds_bpermute_b32 v51, v71, v39
	v_mov_b32_e32 v53, v48
	v_mov_b32_e32 v48, v47
	v_mov_b32_e32 v52, v46
	s_waitcnt lgkmcnt(0)
	v_pk_mul_f32 v[46:47], v[48:49], v[50:51]
	s_nop 0
	v_cndmask_b32_e64 v47, v47, -v47, s[36:37]
	v_cndmask_b32_e64 v46, v46, -v46, s[36:37]
	v_pk_fma_f32 v[38:39], v[38:39], v[52:53], v[46:47]
	ds_bpermute_b32 v46, v71, v40
	ds_bpermute_b32 v47, v71, v41
	v_mov_b32_e32 v49, v44
	v_mov_b32_e32 v44, v43
	v_mov_b32_e32 v48, v42
	s_waitcnt lgkmcnt(0)
	v_pk_mul_f32 v[42:43], v[44:45], v[46:47]
	s_nop 0
	v_cndmask_b32_e64 v43, v43, -v43, s[36:37]
	v_cndmask_b32_e64 v42, v42, -v42, s[36:37]
	v_pk_fma_f32 v[40:41], v[40:41], v[48:49], v[42:43]

.LBB0_948:
	v_mov_b64_e32 v[40:41], v[32:33]
	s_and_b64 vcc, exec, s[40:41]
	v_mov_b64_e32 v[38:39], v[30:31]
	v_mov_b64_e32 v[36:37], v[28:29]
	v_mov_b64_e32 v[34:35], v[26:27]
	s_cbranch_vccnz .LBB0_950
	v_and_b32_e32 v34, 32, v167
	v_cmp_eq_u32_e32 vcc, 0, v34
	v_lshlrev_b32_e32 v35, 2, v0
	s_nop 0
	v_cndmask_b32_e32 v34, v56, v57, vcc
	v_cmp_lt_i32_e32 vcc, v198, v200
	v_lshl_or_b32 v34, v34, 7, v35
	s_nop 0
	v_cndmask_b32_e32 v35, v197, v198, vcc
	v_lshlrev_b32_e32 v43, 2, v35
	v_add_u32_e32 v34, s98, v34
	ds_read_b128 v[44:47], v34 offset:48
	ds_read_b128 v[38:41], v34 offset:32
	ds_read_b128 v[48:51], v34 offset:16
	s_nop 0
	ds_read_b128 v[34:37], v34
	ds_bpermute_b32 v52, v43, v26
	ds_bpermute_b32 v53, v43, v27
	s_waitcnt lgkmcnt(0)
	v_mov_b32_e32 v63, v36
	v_mov_b32_e32 v36, v35
	v_mov_b32_e32 v62, v34
	s_waitcnt lgkmcnt(0)
	v_pk_mul_f32 v[34:35], v[36:37], v[52:53]
	ds_bpermute_b32 v36, v43, v28
	ds_bpermute_b32 v37, v43, v29
	v_mov_b32_e32 v52, v48
	v_mov_b32_e32 v53, v50
	v_mov_b32_e32 v50, v49
	ds_bpermute_b32 v48, v43, v30
	ds_bpermute_b32 v49, v43, v31
	s_waitcnt lgkmcnt(2)
	v_pk_mul_f32 v[36:37], v[50:51], v[36:37]
	v_mov_b32_e32 v51, v40
	v_mov_b32_e32 v40, v39
	v_mov_b32_e32 v50, v38
	s_waitcnt lgkmcnt(0)
	v_pk_mul_f32 v[38:39], v[40:41], v[48:49]
	ds_bpermute_b32 v40, v43, v32
	ds_bpermute_b32 v41, v43, v33
	v_mov_b32_e32 v49, v46
	v_mov_b32_e32 v46, v45
	v_cndmask_b32_e64 v35, v35, -v35, s[38:39]
	v_cndmask_b32_e64 v34, v34, -v34, s[38:39]
	s_waitcnt lgkmcnt(0)
	v_pk_mul_f32 v[40:41], v[46:47], v[40:41]
	v_cndmask_b32_e64 v37, v37, -v37, s[38:39]
	v_cndmask_b32_e64 v36, v36, -v36, s[38:39]
	v_cndmask_b32_e64 v39, v39, -v39, s[38:39]
	v_cndmask_b32_e64 v38, v38, -v38, s[38:39]
	v_mov_b32_e32 v48, v44
	v_cndmask_b32_e64 v41, v41, -v41, s[38:39]
	v_cndmask_b32_e64 v40, v40, -v40, s[38:39]
	v_pk_fma_f32 v[34:35], v[26:27], v[62:63], v[34:35]
	v_pk_fma_f32 v[36:37], v[28:29], v[52:53], v[36:37]
	v_pk_fma_f32 v[38:39], v[30:31], v[50:51], v[38:39]
	v_pk_fma_f32 v[40:41], v[32:33], v[48:49], v[40:41]

.LBB0_951:
	s_mov_b64 s[10:11], 0
	s_cbranch_execz .LBB0_960
	s_and_b64 vcc, exec, s[40:41]
	s_cbranch_vccnz .LBB0_954
	v_and_b32_e32 v34, 32, v167
	v_cmp_eq_u32_e32 vcc, 0, v34
	v_lshlrev_b32_e32 v35, 2, v0
	s_nop 0
	v_cndmask_b32_e32 v34, v56, v57, vcc
	v_cmp_lt_i32_e32 vcc, v198, v200
	v_lshl_or_b32 v46, v34, 7, v35
	s_nop 0
	v_cndmask_b32_e32 v34, v197, v198, vcc
	v_lshlrev_b32_e32 v56, 2, v34
	v_add_u32_e32 v46, s98, v46
	ds_read_b128 v[34:37], v46 offset:48
	ds_read_b128 v[38:41], v46 offset:32
	ds_read_b128 v[42:45], v46 offset:16
	s_nop 0
	ds_read_b128 v[46:49], v46
	ds_bpermute_b32 v50, v56, v26
	ds_bpermute_b32 v51, v56, v27
	s_waitcnt lgkmcnt(0)
	v_mov_b32_e32 v53, v48
	v_mov_b32_e32 v48, v47
	v_mov_b32_e32 v52, v46
	s_waitcnt lgkmcnt(0)
	v_pk_mul_f32 v[46:47], v[48:49], v[50:51]
	v_mov_b32_e32 v49, v44
	v_cndmask_b32_e64 v47, v47, -v47, s[38:39]
	v_cndmask_b32_e64 v46, v46, -v46, s[38:39]
	v_pk_fma_f32 v[26:27], v[26:27], v[52:53], v[46:47]
	ds_bpermute_b32 v46, v56, v28
	ds_bpermute_b32 v47, v56, v29
	v_mov_b32_e32 v44, v43
	v_mov_b32_e32 v48, v42
	s_waitcnt lgkmcnt(0)
	v_pk_mul_f32 v[42:43], v[44:45], v[46:47]
	s_nop 0
	v_cndmask_b32_e64 v43, v43, -v43, s[38:39]
	v_cndmask_b32_e64 v42, v42, -v42, s[38:39]
	v_pk_fma_f32 v[28:29], v[28:29], v[48:49], v[42:43]
	ds_bpermute_b32 v42, v56, v30
	ds_bpermute_b32 v43, v56, v31
	v_mov_b32_e32 v45, v40
	v_mov_b32_e32 v40, v39
	v_mov_b32_e32 v44, v38
	s_waitcnt lgkmcnt(0)
	v_pk_mul_f32 v[38:39], v[40:41], v[42:43]
	s_nop 0
	v_cndmask_b32_e64 v39, v39, -v39, s[38:39]
	v_cndmask_b32_e64 v38, v38, -v38, s[38:39]
	v_pk_fma_f32 v[30:31], v[30:31], v[44:45], v[38:39]
	ds_bpermute_b32 v38, v56, v32
	ds_bpermute_b32 v39, v56, v33
	v_mov_b32_e32 v41, v36
	v_mov_b32_e32 v36, v35
	v_mov_b32_e32 v40, v34
	s_waitcnt lgkmcnt(0)
	v_pk_mul_f32 v[34:35], v[36:37], v[38:39]
	s_nop 0
	v_cndmask_b32_e64 v35, v35, -v35, s[38:39]
	v_cndmask_b32_e64 v34, v34, -v34, s[38:39]
	v_pk_fma_f32 v[32:33], v[32:33], v[40:41], v[34:35]
.LBB0_954:
	s_andn2_b64 vcc, exec, s[0:1]
	s_cbranch_vccnz .LBB0_957
	s_lshl_b32 s6, s91, 3
	v_readlane_b32 s7, v241, 61
	s_or_b32 s6, s6, s7
	s_mul_hi_i32 s7, s6, 0x55555556
	s_lshr_b32 vcc_lo, s7, 31
	s_add_i32 s7, s7, vcc_lo
	s_mul_i32 s7, s7, 3
	s_sub_i32 s6, s6, s7
	s_cmp_lg_u32 s6, 2
	s_cbranch_scc1 .LBB0_957
	v_xor_b32_e32 v34, 16, v197
	v_cmp_lt_i32_e32 vcc, v34, v200
	v_lshlrev_b32_e32 v46, 2, v60
	s_nop 0
	v_cndmask_b32_e32 v34, v197, v34, vcc
	v_lshlrev_b32_e32 v56, 2, v34
	v_add_u32_e32 v46, s99, v46
	ds_read_b128 v[34:37], v46 offset:48
	ds_read_b128 v[38:41], v46 offset:32
	ds_read_b128 v[42:45], v46 offset:16
	s_nop 0
	ds_read_b128 v[46:49], v46
	ds_bpermute_b32 v50, v56, v26
	ds_bpermute_b32 v51, v56, v27
	s_waitcnt lgkmcnt(0)
	v_mov_b32_e32 v53, v48
	v_mov_b32_e32 v48, v47
	v_mov_b32_e32 v52, v46
	s_waitcnt lgkmcnt(0)
	v_pk_mul_f32 v[46:47], v[48:49], v[50:51]
	v_mov_b32_e32 v49, v44
	v_cndmask_b32_e64 v47, v47, -v47, s[36:37]
	v_cndmask_b32_e64 v46, v46, -v46, s[36:37]
	v_pk_fma_f32 v[26:27], v[26:27], v[52:53], v[46:47]
	ds_bpermute_b32 v46, v56, v28
	ds_bpermute_b32 v47, v56, v29
	v_mov_b32_e32 v44, v43
	v_mov_b32_e32 v48, v42
	s_waitcnt lgkmcnt(0)
	v_pk_mul_f32 v[42:43], v[44:45], v[46:47]
	s_nop 0
	v_cndmask_b32_e64 v43, v43, -v43, s[36:37]
	v_cndmask_b32_e64 v42, v42, -v42, s[36:37]
	v_pk_fma_f32 v[28:29], v[28:29], v[48:49], v[42:43]
	ds_bpermute_b32 v42, v56, v30
	ds_bpermute_b32 v43, v56, v31
	v_mov_b32_e32 v45, v40
	v_mov_b32_e32 v40, v39
	v_mov_b32_e32 v44, v38
	s_waitcnt lgkmcnt(0)
	v_pk_mul_f32 v[38:39], v[40:41], v[42:43]
	s_nop 0
	v_cndmask_b32_e64 v39, v39, -v39, s[36:37]
	v_cndmask_b32_e64 v38, v38, -v38, s[36:37]
	v_pk_fma_f32 v[30:31], v[30:31], v[44:45], v[38:39]
	ds_bpermute_b32 v38, v56, v32
	ds_bpermute_b32 v39, v56, v33
	v_mov_b32_e32 v41, v36
	v_mov_b32_e32 v36, v35
	v_mov_b32_e32 v40, v34
	s_waitcnt lgkmcnt(0)
	v_pk_mul_f32 v[34:35], v[36:37], v[38:39]
	s_nop 0
	v_cndmask_b32_e64 v35, v35, -v35, s[36:37]
	v_cndmask_b32_e64 v34, v34, -v34, s[36:37]
	v_pk_fma_f32 v[32:33], v[32:33], v[40:41], v[34:35]

.LBB0_967:
	v_mov_b64_e32 v[32:33], v[24:25]
	s_and_b64 vcc, exec, s[40:41]
	v_mov_b64_e32 v[30:31], v[22:23]
	v_mov_b64_e32 v[28:29], v[20:21]
	v_mov_b64_e32 v[26:27], v[18:19]
	s_cbranch_vccnz .LBB0_969
	v_and_b32_e32 v26, 32, v167
	v_cmp_eq_u32_e32 vcc, 0, v26
	v_lshlrev_b32_e32 v27, 2, v0
	s_nop 0
	v_cndmask_b32_e32 v26, v40, v41, vcc
	v_cmp_lt_i32_e32 vcc, v198, v200
	v_lshl_or_b32 v26, v26, 7, v27
	s_nop 0
	v_cndmask_b32_e32 v27, v197, v198, vcc
	v_lshlrev_b32_e32 v35, 2, v27
	v_add_u32_e32 v26, s98, v26
	ds_read_b128 v[44:47], v26 offset:48
	ds_read_b128 v[30:33], v26 offset:32
	ds_read_b128 v[48:51], v26 offset:16
	s_nop 0
	ds_read_b128 v[26:29], v26
	ds_bpermute_b32 v36, v35, v18
	ds_bpermute_b32 v37, v35, v19
	s_waitcnt lgkmcnt(0)
	v_mov_b32_e32 v53, v28
	v_mov_b32_e32 v28, v27
	v_mov_b32_e32 v52, v26
	s_waitcnt lgkmcnt(0)
	v_pk_mul_f32 v[26:27], v[28:29], v[36:37]
	ds_bpermute_b32 v28, v35, v20
	ds_bpermute_b32 v29, v35, v21
	v_mov_b32_e32 v37, v50
	v_mov_b32_e32 v50, v49
	v_mov_b32_e32 v36, v48
	v_mov_b32_e32 v49, v32
	s_waitcnt lgkmcnt(0)
	v_pk_mul_f32 v[28:29], v[50:51], v[28:29]
	v_mov_b32_e32 v32, v31
	v_cndmask_b32_e64 v29, v29, -v29, s[38:39]
	v_cndmask_b32_e64 v28, v28, -v28, s[38:39]
	v_pk_fma_f32 v[28:29], v[20:21], v[36:37], v[28:29]
	ds_bpermute_b32 v36, v35, v22
	ds_bpermute_b32 v37, v35, v23
	v_mov_b32_e32 v48, v30
	v_cndmask_b32_e64 v27, v27, -v27, s[38:39]
	v_cndmask_b32_e64 v26, v26, -v26, s[38:39]
	v_pk_fma_f32 v[26:27], v[18:19], v[52:53], v[26:27]
	s_waitcnt lgkmcnt(0)
	v_pk_mul_f32 v[30:31], v[32:33], v[36:37]
	ds_bpermute_b32 v32, v35, v24
	ds_bpermute_b32 v33, v35, v25
	v_mov_b32_e32 v37, v46
	v_mov_b32_e32 v46, v45
	v_cndmask_b32_e64 v31, v31, -v31, s[38:39]
	v_cndmask_b32_e64 v30, v30, -v30, s[38:39]
	s_waitcnt lgkmcnt(0)
	v_pk_mul_f32 v[32:33], v[46:47], v[32:33]
	v_mov_b32_e32 v36, v44
	v_cndmask_b32_e64 v33, v33, -v33, s[38:39]
	v_cndmask_b32_e64 v32, v32, -v32, s[38:39]
	v_pk_fma_f32 v[30:31], v[22:23], v[48:49], v[30:31]
	v_pk_fma_f32 v[32:33], v[24:25], v[36:37], v[32:33]

.LBB0_970:
	s_mov_b64 s[10:11], 0
	v_cndmask_b32_e64 v35, v40, v41, s[38:39]
	v_lshlrev_b32_e32 v44, 4, v35
	s_cbranch_execz .LBB0_979
	s_and_b64 vcc, exec, s[40:41]
	s_cbranch_vccnz .LBB0_973
	v_and_b32_e32 v26, 32, v167
	v_cmp_eq_u32_e32 vcc, 0, v26
	v_lshlrev_b32_e32 v27, 2, v0
	s_nop 0
	v_cndmask_b32_e32 v26, v40, v41, vcc
	v_cmp_lt_i32_e32 vcc, v198, v200
	v_lshl_or_b32 v45, v26, 7, v27
	s_nop 0
	v_cndmask_b32_e32 v26, v197, v198, vcc
	v_lshlrev_b32_e32 v54, 2, v26
	v_add_u32_e32 v45, s98, v45
	ds_read_b128 v[26:29], v45 offset:48
	ds_read_b128 v[30:33], v45 offset:32
	ds_read_b128 v[34:37], v45 offset:16
	ds_read_b128 v[46:49], v45
	v_subrev_u32_e32 v45, s98, v45
	ds_bpermute_b32 v50, v54, v18
	ds_bpermute_b32 v51, v54, v19
	s_waitcnt lgkmcnt(0)
	v_mov_b32_e32 v53, v48
	v_mov_b32_e32 v48, v47
	v_mov_b32_e32 v52, v46
	s_waitcnt lgkmcnt(0)
	v_pk_mul_f32 v[46:47], v[48:49], v[50:51]
	v_mov_b32_e32 v49, v36
	v_cndmask_b32_e64 v47, v47, -v47, s[38:39]
	v_cndmask_b32_e64 v46, v46, -v46, s[38:39]
	v_pk_fma_f32 v[18:19], v[18:19], v[52:53], v[46:47]
	ds_bpermute_b32 v46, v54, v20
	ds_bpermute_b32 v47, v54, v21
	v_mov_b32_e32 v36, v35
	v_mov_b32_e32 v48, v34
	s_waitcnt lgkmcnt(0)
	v_pk_mul_f32 v[34:35], v[36:37], v[46:47]
	s_nop 0
	v_cndmask_b32_e64 v35, v35, -v35, s[38:39]
	v_cndmask_b32_e64 v34, v34, -v34, s[38:39]
	v_pk_fma_f32 v[20:21], v[20:21], v[48:49], v[34:35]
	ds_bpermute_b32 v34, v54, v22
	ds_bpermute_b32 v35, v54, v23
	v_mov_b32_e32 v37, v32
	v_mov_b32_e32 v32, v31
	v_mov_b32_e32 v36, v30
	s_waitcnt lgkmcnt(0)
	v_pk_mul_f32 v[30:31], v[32:33], v[34:35]
	s_nop 0
	v_cndmask_b32_e64 v31, v31, -v31, s[38:39]
	v_cndmask_b32_e64 v30, v30, -v30, s[38:39]
	v_pk_fma_f32 v[22:23], v[22:23], v[36:37], v[30:31]
	ds_bpermute_b32 v30, v54, v24
	ds_bpermute_b32 v31, v54, v25
	v_mov_b32_e32 v33, v28
	v_mov_b32_e32 v28, v27
	v_mov_b32_e32 v32, v26
	s_waitcnt lgkmcnt(0)
	v_pk_mul_f32 v[26:27], v[28:29], v[30:31]
	s_nop 0
	v_cndmask_b32_e64 v27, v27, -v27, s[38:39]
	v_cndmask_b32_e64 v26, v26, -v26, s[38:39]
	v_pk_fma_f32 v[24:25], v[24:25], v[32:33], v[26:27]
.LBB0_973:
	s_andn2_b64 vcc, exec, s[0:1]
	s_cbranch_vccnz .LBB0_976
	s_lshl_b32 s6, s91, 3
	v_readlane_b32 s7, v241, 60
	s_or_b32 s6, s6, s7
	s_mul_hi_i32 s7, s6, 0x55555556
	s_lshr_b32 vcc_lo, s7, 31
	s_add_i32 s7, s7, vcc_lo
	s_mul_i32 s7, s7, 3
	s_sub_i32 s6, s6, s7
	s_cmp_lg_u32 s6, 2
	s_cbranch_scc1 .LBB0_976
	v_xor_b32_e32 v26, 16, v197
	v_cmp_lt_i32_e32 vcc, v26, v200
	v_lshlrev_b32_e32 v45, 2, v44
	s_nop 0
	v_cndmask_b32_e32 v26, v197, v26, vcc
	v_lshlrev_b32_e32 v54, 2, v26
	v_add_u32_e32 v45, s99, v45
	ds_read_b128 v[26:29], v45 offset:48
	ds_read_b128 v[30:33], v45 offset:32
	ds_read_b128 v[34:37], v45 offset:16
	ds_read_b128 v[46:49], v45
	v_subrev_u32_e32 v45, s99, v45
	ds_bpermute_b32 v50, v54, v18
	ds_bpermute_b32 v51, v54, v19
	s_waitcnt lgkmcnt(0)
	v_mov_b32_e32 v53, v48
	v_mov_b32_e32 v48, v47
	v_mov_b32_e32 v52, v46
	s_waitcnt lgkmcnt(0)
	v_pk_mul_f32 v[46:47], v[48:49], v[50:51]
	v_mov_b32_e32 v49, v36
	v_cndmask_b32_e64 v47, v47, -v47, s[36:37]
	v_cndmask_b32_e64 v46, v46, -v46, s[36:37]
	v_pk_fma_f32 v[18:19], v[18:19], v[52:53], v[46:47]
	ds_bpermute_b32 v46, v54, v20
	ds_bpermute_b32 v47, v54, v21
	v_mov_b32_e32 v36, v35
	v_mov_b32_e32 v48, v34
	s_waitcnt lgkmcnt(0)
	v_pk_mul_f32 v[34:35], v[36:37], v[46:47]
	s_nop 0
	v_cndmask_b32_e64 v35, v35, -v35, s[36:37]
	v_cndmask_b32_e64 v34, v34, -v34, s[36:37]
	v_pk_fma_f32 v[20:21], v[20:21], v[48:49], v[34:35]
	ds_bpermute_b32 v34, v54, v22
	ds_bpermute_b32 v35, v54, v23
	v_mov_b32_e32 v37, v32
	v_mov_b32_e32 v32, v31
	v_mov_b32_e32 v36, v30
	s_waitcnt lgkmcnt(0)
	v_pk_mul_f32 v[30:31], v[32:33], v[34:35]
	s_nop 0
	v_cndmask_b32_e64 v31, v31, -v31, s[36:37]
	v_cndmask_b32_e64 v30, v30, -v30, s[36:37]
	v_pk_fma_f32 v[22:23], v[22:23], v[36:37], v[30:31]
	ds_bpermute_b32 v30, v54, v24
	ds_bpermute_b32 v31, v54, v25
	v_mov_b32_e32 v33, v28
	v_mov_b32_e32 v28, v27
	v_mov_b32_e32 v32, v26
	s_waitcnt lgkmcnt(0)
	v_pk_mul_f32 v[26:27], v[28:29], v[30:31]
	s_nop 0
	v_cndmask_b32_e64 v27, v27, -v27, s[36:37]
	v_cndmask_b32_e64 v26, v26, -v26, s[36:37]
	v_pk_fma_f32 v[24:25], v[24:25], v[32:33], v[26:27]

.LBB0_984:
	v_mov_b64_e32 v[24:25], v[16:17]
	s_and_b64 vcc, exec, s[40:41]
	v_mov_b64_e32 v[22:23], v[14:15]
	v_mov_b64_e32 v[20:21], v[12:13]
	v_mov_b64_e32 v[18:19], v[10:11]
	s_cbranch_vccnz .LBB0_986
	v_and_b32_e32 v18, 32, v167
	v_cmp_eq_u32_e32 vcc, 0, v18
	v_lshlrev_b32_e32 v19, 2, v0
	s_nop 0
	v_cndmask_b32_e32 v18, v40, v41, vcc
	v_cmp_lt_i32_e32 vcc, v198, v200
	v_lshl_or_b32 v18, v18, 7, v19
	s_nop 0
	v_cndmask_b32_e32 v19, v197, v198, vcc
	v_lshlrev_b32_e32 v27, 2, v19
	v_add_u32_e32 v18, s98, v18
	ds_read_b128 v[28:31], v18 offset:48
	ds_read_b128 v[22:25], v18 offset:32
	ds_read_b128 v[32:35], v18 offset:16
	s_nop 0
	ds_read_b128 v[18:21], v18
	ds_bpermute_b32 v36, v27, v10
	ds_bpermute_b32 v37, v27, v11
	s_waitcnt lgkmcnt(0)
	v_mov_b32_e32 v47, v20
	v_mov_b32_e32 v20, v19
	v_mov_b32_e32 v46, v18
	s_waitcnt lgkmcnt(0)
	v_pk_mul_f32 v[18:19], v[20:21], v[36:37]
	ds_bpermute_b32 v20, v27, v12
	ds_bpermute_b32 v21, v27, v13
	v_mov_b32_e32 v36, v32
	v_mov_b32_e32 v37, v34
	v_mov_b32_e32 v34, v33
	ds_bpermute_b32 v32, v27, v14
	ds_bpermute_b32 v33, v27, v15
	s_waitcnt lgkmcnt(2)
	v_pk_mul_f32 v[20:21], v[34:35], v[20:21]
	v_mov_b32_e32 v35, v24
	v_mov_b32_e32 v24, v23
	v_mov_b32_e32 v34, v22
	s_waitcnt lgkmcnt(0)
	v_pk_mul_f32 v[22:23], v[24:25], v[32:33]
	ds_bpermute_b32 v24, v27, v16
	ds_bpermute_b32 v25, v27, v17
	v_mov_b32_e32 v33, v30
	v_mov_b32_e32 v30, v29
	v_cndmask_b32_e64 v19, v19, -v19, s[38:39]
	v_cndmask_b32_e64 v18, v18, -v18, s[38:39]
	s_waitcnt lgkmcnt(0)
	v_pk_mul_f32 v[24:25], v[30:31], v[24:25]
	v_cndmask_b32_e64 v21, v21, -v21, s[38:39]
	v_cndmask_b32_e64 v20, v20, -v20, s[38:39]
	v_cndmask_b32_e64 v23, v23, -v23, s[38:39]
	v_cndmask_b32_e64 v22, v22, -v22, s[38:39]
	v_mov_b32_e32 v32, v28
	v_cndmask_b32_e64 v25, v25, -v25, s[38:39]
	v_cndmask_b32_e64 v24, v24, -v24, s[38:39]
	v_pk_fma_f32 v[18:19], v[10:11], v[46:47], v[18:19]
	v_pk_fma_f32 v[20:21], v[12:13], v[36:37], v[20:21]
	v_pk_fma_f32 v[22:23], v[14:15], v[34:35], v[22:23]
	v_pk_fma_f32 v[24:25], v[16:17], v[32:33], v[24:25]

.LBB0_987:
	s_mov_b64 s[10:11], 0
	s_cbranch_execz .LBB0_996
	s_and_b64 vcc, exec, s[40:41]
	s_cbranch_vccnz .LBB0_990
	v_and_b32_e32 v18, 32, v167
	v_cmp_eq_u32_e32 vcc, 0, v18
	v_lshlrev_b32_e32 v19, 2, v0
	s_nop 0
	v_cndmask_b32_e32 v18, v40, v41, vcc
	v_cmp_lt_i32_e32 vcc, v198, v200
	v_lshl_or_b32 v30, v18, 7, v19
	s_nop 0
	v_cndmask_b32_e32 v18, v197, v198, vcc
	v_lshlrev_b32_e32 v40, 2, v18
	v_add_u32_e32 v30, s98, v30
	ds_read_b128 v[18:21], v30 offset:48
	ds_read_b128 v[22:25], v30 offset:32
	ds_read_b128 v[26:29], v30 offset:16
	s_nop 0
	ds_read_b128 v[30:33], v30
	ds_bpermute_b32 v34, v40, v10
	ds_bpermute_b32 v35, v40, v11
	s_waitcnt lgkmcnt(0)
	v_mov_b32_e32 v37, v32
	v_mov_b32_e32 v32, v31
	v_mov_b32_e32 v36, v30
	s_waitcnt lgkmcnt(0)
	v_pk_mul_f32 v[30:31], v[32:33], v[34:35]
	v_mov_b32_e32 v33, v28
	v_cndmask_b32_e64 v31, v31, -v31, s[38:39]
	v_cndmask_b32_e64 v30, v30, -v30, s[38:39]
	v_pk_fma_f32 v[10:11], v[10:11], v[36:37], v[30:31]
	ds_bpermute_b32 v30, v40, v12
	ds_bpermute_b32 v31, v40, v13
	v_mov_b32_e32 v28, v27
	v_mov_b32_e32 v32, v26
	s_waitcnt lgkmcnt(0)
	v_pk_mul_f32 v[26:27], v[28:29], v[30:31]
	s_nop 0
	v_cndmask_b32_e64 v27, v27, -v27, s[38:39]
	v_cndmask_b32_e64 v26, v26, -v26, s[38:39]
	v_pk_fma_f32 v[12:13], v[12:13], v[32:33], v[26:27]
	ds_bpermute_b32 v26, v40, v14
	ds_bpermute_b32 v27, v40, v15
	v_mov_b32_e32 v29, v24
	v_mov_b32_e32 v24, v23
	v_mov_b32_e32 v28, v22
	s_waitcnt lgkmcnt(0)
	v_pk_mul_f32 v[22:23], v[24:25], v[26:27]
	s_nop 0
	v_cndmask_b32_e64 v23, v23, -v23, s[38:39]
	v_cndmask_b32_e64 v22, v22, -v22, s[38:39]
	v_pk_fma_f32 v[14:15], v[14:15], v[28:29], v[22:23]
	ds_bpermute_b32 v22, v40, v16
	ds_bpermute_b32 v23, v40, v17
	v_mov_b32_e32 v25, v20
	v_mov_b32_e32 v20, v19
	v_mov_b32_e32 v24, v18
	s_waitcnt lgkmcnt(0)
	v_pk_mul_f32 v[18:19], v[20:21], v[22:23]
	s_nop 0
	v_cndmask_b32_e64 v19, v19, -v19, s[38:39]
	v_cndmask_b32_e64 v18, v18, -v18, s[38:39]
	v_pk_fma_f32 v[16:17], v[16:17], v[24:25], v[18:19]
.LBB0_990:
	s_andn2_b64 vcc, exec, s[0:1]
	s_cbranch_vccnz .LBB0_993
	s_lshl_b32 s6, s91, 3
	v_readlane_b32 s7, v241, 61
	s_or_b32 s6, s6, s7
	s_mul_hi_i32 s7, s6, 0x55555556
	s_lshr_b32 vcc_lo, s7, 31
	s_add_i32 s7, s7, vcc_lo
	s_mul_i32 s7, s7, 3
	s_sub_i32 s6, s6, s7
	s_cmp_lg_u32 s6, 2
	s_cbranch_scc1 .LBB0_993
	v_xor_b32_e32 v18, 16, v197
	v_cmp_lt_i32_e32 vcc, v18, v200
	v_lshlrev_b32_e32 v30, 2, v44
	s_nop 0
	v_cndmask_b32_e32 v18, v197, v18, vcc
	v_lshlrev_b32_e32 v40, 2, v18
	v_add_u32_e32 v30, s99, v30
	ds_read_b128 v[18:21], v30 offset:48
	ds_read_b128 v[22:25], v30 offset:32
	ds_read_b128 v[26:29], v30 offset:16
	s_nop 0
	ds_read_b128 v[30:33], v30
	ds_bpermute_b32 v34, v40, v10
	ds_bpermute_b32 v35, v40, v11
	s_waitcnt lgkmcnt(0)
	v_mov_b32_e32 v37, v32
	v_mov_b32_e32 v32, v31
	v_mov_b32_e32 v36, v30
	s_waitcnt lgkmcnt(0)
	v_pk_mul_f32 v[30:31], v[32:33], v[34:35]
	v_mov_b32_e32 v33, v28
	v_cndmask_b32_e64 v31, v31, -v31, s[36:37]
	v_cndmask_b32_e64 v30, v30, -v30, s[36:37]
	v_pk_fma_f32 v[10:11], v[10:11], v[36:37], v[30:31]
	ds_bpermute_b32 v30, v40, v12
	ds_bpermute_b32 v31, v40, v13
	v_mov_b32_e32 v28, v27
	v_mov_b32_e32 v32, v26
	s_waitcnt lgkmcnt(0)
	v_pk_mul_f32 v[26:27], v[28:29], v[30:31]
	s_nop 0
	v_cndmask_b32_e64 v27, v27, -v27, s[36:37]
	v_cndmask_b32_e64 v26, v26, -v26, s[36:37]
	v_pk_fma_f32 v[12:13], v[12:13], v[32:33], v[26:27]
	ds_bpermute_b32 v26, v40, v14
	ds_bpermute_b32 v27, v40, v15
	v_mov_b32_e32 v29, v24
	v_mov_b32_e32 v24, v23
	v_mov_b32_e32 v28, v22
	s_waitcnt lgkmcnt(0)
	v_pk_mul_f32 v[22:23], v[24:25], v[26:27]
	s_nop 0
	v_cndmask_b32_e64 v23, v23, -v23, s[36:37]
	v_cndmask_b32_e64 v22, v22, -v22, s[36:37]
	v_pk_fma_f32 v[14:15], v[14:15], v[28:29], v[22:23]
	ds_bpermute_b32 v22, v40, v16
	ds_bpermute_b32 v23, v40, v17
	v_mov_b32_e32 v25, v20
	v_mov_b32_e32 v20, v19
	v_mov_b32_e32 v24, v18
	s_waitcnt lgkmcnt(0)
	v_pk_mul_f32 v[18:19], v[20:21], v[22:23]
	s_nop 0
	v_cndmask_b32_e64 v19, v19, -v19, s[36:37]
	v_cndmask_b32_e64 v18, v18, -v18, s[36:37]
	v_pk_fma_f32 v[16:17], v[16:17], v[24:25], v[18:19]

.LBB0_1003:
	v_mov_b64_e32 v[16:17], v[8:9]
	s_and_b64 vcc, exec, s[40:41]
	v_mov_b64_e32 v[14:15], v[6:7]
	v_mov_b64_e32 v[12:13], v[4:5]
	v_mov_b64_e32 v[10:11], v[2:3]
	s_cbranch_vccnz .LBB0_1005
	v_and_b32_e32 v10, 32, v167
	v_cmp_eq_u32_e32 vcc, 0, v10
	v_lshlrev_b32_e32 v11, 2, v0
	s_nop 0
	v_cndmask_b32_e32 v10, v22, v23, vcc
	v_lshl_or_b32 v25, v10, 7, v11
	v_add_u32_e32 v25, s98, v25
	ds_read_b128 v[16:19], v25 offset:48
	ds_read_b128 v[28:31], v25 offset:32
	ds_read_b128 v[12:15], v25 offset:16
	ds_read_b128 v[32:35], v25
	v_subrev_u32_e32 v25, s98, v25
	v_cmp_lt_i32_e32 vcc, v198, v200
	s_waitcnt lgkmcnt(0)
	v_mov_b32_e32 v36, v32
	v_cndmask_b32_e32 v10, v197, v198, vcc
	v_lshlrev_b32_e32 v27, 2, v10
	ds_bpermute_b32 v10, v27, v2
	ds_bpermute_b32 v11, v27, v3
	v_mov_b32_e32 v37, v34
	v_mov_b32_e32 v34, v33
	ds_bpermute_b32 v32, v27, v4
	ds_bpermute_b32 v33, v27, v5
	s_waitcnt lgkmcnt(0)
	v_pk_mul_f32 v[10:11], v[34:35], v[10:11]
	v_mov_b32_e32 v35, v14
	v_mov_b32_e32 v14, v13
	v_mov_b32_e32 v34, v12
	v_pk_mul_f32 v[12:13], v[14:15], v[32:33]
	ds_bpermute_b32 v14, v27, v6
	ds_bpermute_b32 v15, v27, v7
	v_mov_b32_e32 v32, v28
	v_mov_b32_e32 v33, v30
	v_mov_b32_e32 v30, v29
	ds_bpermute_b32 v28, v27, v8
	ds_bpermute_b32 v29, v27, v9
	s_waitcnt lgkmcnt(2)
	v_pk_mul_f32 v[14:15], v[30:31], v[14:15]
	v_mov_b32_e32 v31, v18
	v_mov_b32_e32 v18, v17
	v_mov_b32_e32 v30, v16
	s_waitcnt lgkmcnt(0)
	v_pk_mul_f32 v[16:17], v[18:19], v[28:29]
	v_cndmask_b32_e64 v11, v11, -v11, s[38:39]
	v_cndmask_b32_e64 v10, v10, -v10, s[38:39]
	v_cndmask_b32_e64 v13, v13, -v13, s[38:39]
	v_cndmask_b32_e64 v12, v12, -v12, s[38:39]
	v_cndmask_b32_e64 v15, v15, -v15, s[38:39]
	v_cndmask_b32_e64 v14, v14, -v14, s[38:39]
	v_cndmask_b32_e64 v17, v17, -v17, s[38:39]
	v_cndmask_b32_e64 v16, v16, -v16, s[38:39]
	v_pk_fma_f32 v[10:11], v[2:3], v[36:37], v[10:11]
	v_pk_fma_f32 v[12:13], v[4:5], v[34:35], v[12:13]
	v_pk_fma_f32 v[14:15], v[6:7], v[32:33], v[14:15]
	v_pk_fma_f32 v[16:17], v[8:9], v[30:31], v[16:17]

.LBB0_1007:
	s_mov_b64 s[10:11], 0
	v_cndmask_b32_e64 v25, v22, v23, s[38:39]
	v_lshlrev_b32_e32 v25, 4, v25
	s_cbranch_execz .LBB0_1006
	s_and_b64 vcc, exec, s[40:41]
	s_cbranch_vccnz .LBB0_1010
	v_and_b32_e32 v10, 32, v167
	v_cmp_eq_u32_e32 vcc, 0, v10
	v_lshlrev_b32_e32 v11, 2, v0
	s_nop 0
	v_cndmask_b32_e32 v10, v22, v23, vcc
	v_cmp_lt_i32_e32 vcc, v198, v200
	v_lshl_or_b32 v27, v10, 7, v11
	s_nop 0
	v_cndmask_b32_e32 v10, v197, v198, vcc
	v_lshlrev_b32_e32 v38, 2, v10
	v_add_u32_e32 v27, s98, v27
	ds_read_b128 v[10:13], v27 offset:48
	ds_read_b128 v[14:17], v27 offset:32
	ds_read_b128 v[28:31], v27 offset:16
	ds_read_b128 v[32:35], v27
	v_subrev_u32_e32 v27, s98, v27
	ds_bpermute_b32 v18, v38, v2
	ds_bpermute_b32 v19, v38, v3
	s_waitcnt lgkmcnt(0)
	v_mov_b32_e32 v37, v34
	v_mov_b32_e32 v34, v33
	s_waitcnt lgkmcnt(0)
	v_pk_mul_f32 v[18:19], v[34:35], v[18:19]
	v_mov_b32_e32 v36, v32
	v_cndmask_b32_e64 v19, v19, -v19, s[38:39]
	v_cndmask_b32_e64 v18, v18, -v18, s[38:39]
	v_pk_fma_f32 v[2:3], v[2:3], v[36:37], v[18:19]
	ds_bpermute_b32 v18, v38, v4
	ds_bpermute_b32 v19, v38, v5
	v_mov_b32_e32 v33, v30
	v_mov_b32_e32 v30, v29
	v_mov_b32_e32 v32, v28
	v_mov_b32_e32 v29, v16
	s_waitcnt lgkmcnt(0)
	v_pk_mul_f32 v[18:19], v[30:31], v[18:19]
	v_mov_b32_e32 v16, v15
	v_cndmask_b32_e64 v19, v19, -v19, s[38:39]
	v_cndmask_b32_e64 v18, v18, -v18, s[38:39]
	v_pk_fma_f32 v[4:5], v[4:5], v[32:33], v[18:19]
	ds_bpermute_b32 v18, v38, v6
	ds_bpermute_b32 v19, v38, v7
	v_mov_b32_e32 v28, v14
	s_waitcnt lgkmcnt(0)
	v_pk_mul_f32 v[14:15], v[16:17], v[18:19]
	s_nop 0
	v_cndmask_b32_e64 v15, v15, -v15, s[38:39]
	v_cndmask_b32_e64 v14, v14, -v14, s[38:39]
	v_pk_fma_f32 v[6:7], v[6:7], v[28:29], v[14:15]
	ds_bpermute_b32 v14, v38, v8
	ds_bpermute_b32 v15, v38, v9
	v_mov_b32_e32 v17, v12
	v_mov_b32_e32 v12, v11
	v_mov_b32_e32 v16, v10
	s_waitcnt lgkmcnt(0)
	v_pk_mul_f32 v[10:11], v[12:13], v[14:15]
	s_nop 0
	v_cndmask_b32_e64 v11, v11, -v11, s[38:39]
	v_cndmask_b32_e64 v10, v10, -v10, s[38:39]
	v_pk_fma_f32 v[8:9], v[8:9], v[16:17], v[10:11]
.LBB0_1010:
	s_andn2_b64 vcc, exec, s[0:1]
	s_cbranch_vccnz .LBB0_1013
	s_lshl_b32 s6, s91, 3
	v_readlane_b32 s7, v241, 60
	s_or_b32 s6, s6, s7
	s_mul_hi_i32 s7, s6, 0x55555556
	s_lshr_b32 s44, s7, 31
	s_add_i32 s7, s7, s44
	s_mul_i32 s7, s7, 3
	s_sub_i32 s6, s6, s7
	s_cmp_lg_u32 s6, 2
	s_cbranch_scc1 .LBB0_1013
	v_xor_b32_e32 v10, 16, v197
	v_cmp_lt_i32_e32 vcc, v10, v200
	v_lshlrev_b32_e32 v27, 2, v25
	s_nop 0
	v_cndmask_b32_e32 v10, v197, v10, vcc
	v_lshlrev_b32_e32 v38, 2, v10
	v_add_u32_e32 v27, s99, v27
	ds_read_b128 v[10:13], v27 offset:48
	ds_read_b128 v[14:17], v27 offset:32
	ds_read_b128 v[28:31], v27 offset:16
	ds_read_b128 v[32:35], v27
	v_subrev_u32_e32 v27, s99, v27
	ds_bpermute_b32 v18, v38, v2
	ds_bpermute_b32 v19, v38, v3
	s_waitcnt lgkmcnt(0)
	v_mov_b32_e32 v37, v34
	v_mov_b32_e32 v34, v33
	s_waitcnt lgkmcnt(0)
	v_pk_mul_f32 v[18:19], v[34:35], v[18:19]
	v_mov_b32_e32 v36, v32
	v_cndmask_b32_e64 v19, v19, -v19, s[36:37]
	v_cndmask_b32_e64 v18, v18, -v18, s[36:37]
	v_pk_fma_f32 v[2:3], v[2:3], v[36:37], v[18:19]
	ds_bpermute_b32 v18, v38, v4
	ds_bpermute_b32 v19, v38, v5
	v_mov_b32_e32 v33, v30
	v_mov_b32_e32 v30, v29
	v_mov_b32_e32 v32, v28
	v_mov_b32_e32 v29, v16
	s_waitcnt lgkmcnt(0)
	v_pk_mul_f32 v[18:19], v[30:31], v[18:19]
	v_mov_b32_e32 v16, v15
	v_cndmask_b32_e64 v19, v19, -v19, s[36:37]
	v_cndmask_b32_e64 v18, v18, -v18, s[36:37]
	v_pk_fma_f32 v[4:5], v[4:5], v[32:33], v[18:19]
	ds_bpermute_b32 v18, v38, v6
	ds_bpermute_b32 v19, v38, v7
	v_mov_b32_e32 v28, v14
	s_waitcnt lgkmcnt(0)
	v_pk_mul_f32 v[14:15], v[16:17], v[18:19]
	s_nop 0
	v_cndmask_b32_e64 v15, v15, -v15, s[36:37]
	v_cndmask_b32_e64 v14, v14, -v14, s[36:37]
	v_pk_fma_f32 v[6:7], v[6:7], v[28:29], v[14:15]
	ds_bpermute_b32 v14, v38, v8
	ds_bpermute_b32 v15, v38, v9
	v_mov_b32_e32 v17, v12
	v_mov_b32_e32 v12, v11
	v_mov_b32_e32 v16, v10
	s_waitcnt lgkmcnt(0)
	v_pk_mul_f32 v[10:11], v[12:13], v[14:15]
	s_nop 0
	v_cndmask_b32_e64 v11, v11, -v11, s[36:37]
	v_cndmask_b32_e64 v10, v10, -v10, s[36:37]
	v_pk_fma_f32 v[8:9], v[8:9], v[16:17], v[10:11]

.LBB0_1021:
	s_and_b64 vcc, exec, s[40:41]
	s_cbranch_vccnz .LBB0_1025
	v_and_b32_e32 v2, 32, v167
	v_cmp_eq_u32_e32 vcc, 0, v2
	v_lshlrev_b32_e32 v3, 2, v0
	s_nop 0
	v_cndmask_b32_e32 v2, v22, v23, vcc
	v_lshl_or_b32 v16, v2, 7, v3
	v_add_u32_e32 v16, s98, v16
	ds_read_b128 v[8:11], v16 offset:48
	ds_read_b128 v[12:15], v16 offset:32
	ds_read_b128 v[4:7], v16 offset:16
	s_nop 0
	ds_read_b128 v[16:19], v16
	v_cmp_lt_i32_e32 vcc, v198, v200
	s_waitcnt lgkmcnt(0)
	v_mov_b32_e32 v28, v16
	v_cndmask_b32_e32 v2, v197, v198, vcc
	v_lshlrev_b32_e32 v27, 2, v2
	ds_bpermute_b32 v2, v27, v134
	ds_bpermute_b32 v3, v27, v135
	v_mov_b32_e32 v29, v18
	v_mov_b32_e32 v18, v17
	ds_bpermute_b32 v16, v27, v136
	ds_bpermute_b32 v17, v27, v137
	s_waitcnt lgkmcnt(0)
	v_pk_mul_f32 v[2:3], v[18:19], v[2:3]
	v_mov_b32_e32 v19, v6
	v_mov_b32_e32 v6, v5
	v_mov_b32_e32 v18, v4
	v_pk_mul_f32 v[4:5], v[6:7], v[16:17]
	ds_bpermute_b32 v6, v27, v130
	ds_bpermute_b32 v7, v27, v131
	v_mov_b32_e32 v16, v12
	v_mov_b32_e32 v17, v14
	v_mov_b32_e32 v14, v13
	ds_bpermute_b32 v12, v27, v132
	ds_bpermute_b32 v13, v27, v133
	s_waitcnt lgkmcnt(2)
	v_pk_mul_f32 v[6:7], v[14:15], v[6:7]
	v_mov_b32_e32 v15, v10
	v_mov_b32_e32 v10, v9
	v_mov_b32_e32 v14, v8
	s_waitcnt lgkmcnt(0)
	v_pk_mul_f32 v[8:9], v[10:11], v[12:13]
	v_cndmask_b32_e64 v3, v3, -v3, s[38:39]
	v_cndmask_b32_e64 v2, v2, -v2, s[38:39]
	v_cndmask_b32_e64 v5, v5, -v5, s[38:39]
	v_cndmask_b32_e64 v4, v4, -v4, s[38:39]
	v_cndmask_b32_e64 v7, v7, -v7, s[38:39]
	v_cndmask_b32_e64 v6, v6, -v6, s[38:39]
	v_cndmask_b32_e64 v9, v9, -v9, s[38:39]
	v_cndmask_b32_e64 v8, v8, -v8, s[38:39]
	v_pk_fma_f32 v[2:3], v[134:135], v[28:29], v[2:3]
	v_pk_fma_f32 v[4:5], v[136:137], v[18:19], v[4:5]
	v_pk_fma_f32 v[6:7], v[130:131], v[16:17], v[6:7]
	v_pk_fma_f32 v[8:9], v[132:133], v[14:15], v[8:9]
	s_branch .LBB0_1026

.LBB0_1027:
	s_and_b64 vcc, exec, s[40:41]
	s_cbranch_vccnz .LBB0_1029
	v_and_b32_e32 v2, 32, v167
	v_cmp_eq_u32_e32 vcc, 0, v2
	v_lshlrev_b32_e32 v0, 2, v0
	s_nop 0
	v_cndmask_b32_e32 v2, v22, v23, vcc
	v_cmp_lt_i32_e32 vcc, v198, v200
	v_lshl_or_b32 v0, v2, 7, v0
	s_nop 0
	v_cndmask_b32_e32 v2, v197, v198, vcc
	v_lshlrev_b32_e32 v24, 2, v2
	v_add_u32_e32 v0, s98, v0
	ds_read_b128 v[2:5], v0 offset:48
	ds_read_b128 v[6:9], v0 offset:32
	ds_read_b128 v[10:13], v0 offset:16
	ds_read_b128 v[14:17], v0
	v_subrev_u32_e32 v0, s98, v0
	ds_bpermute_b32 v18, v24, v134
	ds_bpermute_b32 v19, v24, v135
	s_waitcnt lgkmcnt(0)
	v_mov_b32_e32 v23, v16
	v_mov_b32_e32 v16, v15
	v_mov_b32_e32 v22, v14
	s_waitcnt lgkmcnt(0)
	v_pk_mul_f32 v[14:15], v[16:17], v[18:19]
	v_mov_b32_e32 v17, v12
	v_cndmask_b32_e64 v15, v15, -v15, s[38:39]
	v_cndmask_b32_e64 v14, v14, -v14, s[38:39]
	v_pk_fma_f32 v[134:135], v[134:135], v[22:23], v[14:15]
	ds_bpermute_b32 v14, v24, v136
	ds_bpermute_b32 v15, v24, v137
	v_mov_b32_e32 v12, v11
	v_mov_b32_e32 v16, v10
	s_waitcnt lgkmcnt(0)
	v_pk_mul_f32 v[10:11], v[12:13], v[14:15]
	s_nop 0
	v_cndmask_b32_e64 v11, v11, -v11, s[38:39]
	v_cndmask_b32_e64 v10, v10, -v10, s[38:39]
	v_pk_fma_f32 v[136:137], v[136:137], v[16:17], v[10:11]
	ds_bpermute_b32 v10, v24, v130
	ds_bpermute_b32 v11, v24, v131
	v_mov_b32_e32 v13, v8
	v_mov_b32_e32 v8, v7
	v_mov_b32_e32 v12, v6
	s_waitcnt lgkmcnt(0)
	v_pk_mul_f32 v[6:7], v[8:9], v[10:11]
	s_nop 0
	v_cndmask_b32_e64 v7, v7, -v7, s[38:39]
	v_cndmask_b32_e64 v6, v6, -v6, s[38:39]
	v_pk_fma_f32 v[130:131], v[130:131], v[12:13], v[6:7]
	ds_bpermute_b32 v6, v24, v132
	ds_bpermute_b32 v7, v24, v133
	v_mov_b32_e32 v9, v4
	v_mov_b32_e32 v4, v3
	v_mov_b32_e32 v8, v2
	s_waitcnt lgkmcnt(0)
	v_pk_mul_f32 v[2:3], v[4:5], v[6:7]
	s_nop 0
	v_cndmask_b32_e64 v3, v3, -v3, s[38:39]
	v_cndmask_b32_e64 v2, v2, -v2, s[38:39]
	v_pk_fma_f32 v[132:133], v[132:133], v[8:9], v[2:3]
.LBB0_1029:
	s_andn2_b64 vcc, exec, s[0:1]
	s_cbranch_vccnz .LBB0_1032
	s_lshl_b32 s0, s91, 3
	v_readlane_b32 s1, v241, 61
	s_or_b32 s0, s0, s1
	s_mul_hi_i32 s1, s0, 0x55555556
	s_lshr_b32 s6, s1, 31
	s_add_i32 s1, s1, s6
	s_mul_i32 s1, s1, 3
	s_sub_i32 s0, s0, s1
	s_cmp_lg_u32 s0, 2
	s_cbranch_scc1 .LBB0_1032
	v_xor_b32_e32 v2, 16, v197
	v_cmp_lt_i32_e32 vcc, v2, v200
	v_lshlrev_b32_e32 v0, 2, v25
	s_nop 0
	v_cndmask_b32_e32 v2, v197, v2, vcc
	v_lshlrev_b32_e32 v24, 2, v2
	v_add_u32_e32 v0, s99, v0
	ds_read_b128 v[2:5], v0 offset:48
	ds_read_b128 v[6:9], v0 offset:32
	ds_read_b128 v[10:13], v0 offset:16
	ds_read_b128 v[14:17], v0
	v_subrev_u32_e32 v0, s99, v0
	ds_bpermute_b32 v18, v24, v134
	ds_bpermute_b32 v19, v24, v135
	s_waitcnt lgkmcnt(0)
	v_mov_b32_e32 v23, v16
	v_mov_b32_e32 v16, v15
	v_mov_b32_e32 v22, v14
	s_waitcnt lgkmcnt(0)
	v_pk_mul_f32 v[14:15], v[16:17], v[18:19]
	v_mov_b32_e32 v17, v12
	v_cndmask_b32_e64 v15, v15, -v15, s[36:37]
	v_cndmask_b32_e64 v14, v14, -v14, s[36:37]
	v_pk_fma_f32 v[134:135], v[134:135], v[22:23], v[14:15]
	ds_bpermute_b32 v14, v24, v136
	ds_bpermute_b32 v15, v24, v137
	v_mov_b32_e32 v12, v11
	v_mov_b32_e32 v16, v10
	s_waitcnt lgkmcnt(0)
	v_pk_mul_f32 v[10:11], v[12:13], v[14:15]
	s_nop 0
	v_cndmask_b32_e64 v11, v11, -v11, s[36:37]
	v_cndmask_b32_e64 v10, v10, -v10, s[36:37]
	v_pk_fma_f32 v[136:137], v[136:137], v[16:17], v[10:11]
	ds_bpermute_b32 v10, v24, v130
	ds_bpermute_b32 v11, v24, v131
	v_mov_b32_e32 v13, v8
	v_mov_b32_e32 v8, v7
	v_mov_b32_e32 v12, v6
	s_waitcnt lgkmcnt(0)
	v_pk_mul_f32 v[6:7], v[8:9], v[10:11]
	s_nop 0
	v_cndmask_b32_e64 v7, v7, -v7, s[36:37]
	v_cndmask_b32_e64 v6, v6, -v6, s[36:37]
	v_pk_fma_f32 v[130:131], v[130:131], v[12:13], v[6:7]
	ds_bpermute_b32 v6, v24, v132
	ds_bpermute_b32 v7, v24, v133
	v_mov_b32_e32 v9, v4
	v_mov_b32_e32 v4, v3
	v_mov_b32_e32 v8, v2
	s_waitcnt lgkmcnt(0)
	v_pk_mul_f32 v[2:3], v[4:5], v[6:7]
	s_nop 0
	v_cndmask_b32_e64 v3, v3, -v3, s[36:37]
	v_cndmask_b32_e64 v2, v2, -v2, s[36:37]
	v_pk_fma_f32 v[132:133], v[132:133], v[8:9], v[2:3]
